# v46 + the next-tile select block (s_cmp + 10 s_cselect) moved from phase 1's load segment to phase 2's
# speedup vs baseline: 1.0095x; 1.0095x over previous
; #define PG8_WAIT_V(n) asm volatile("s_waitcnt vmcnt(" #n ")" ::: "memory")
; template <class Epi, bool ALIGN_EPI, bool SP2, class Hook>
; __device__ __forceinline__ void gemm_phase(LAS unsigned char* lds, const Gemm g, const StaticOrder& S, const Epi& E, Acc& acc, const bool fresh, const Hook& H, const int wave_id) {
;     ...
;             const bool last = (t == nt - 2);
;             const Src a1 = cA + (size_t)(t + 1) * kstep;
;             const Src a2 = last ? nA : cA + (size_t)(t + 2) * kstep, b2 = last ? nB : cB + (size_t)(t + 2) * kstep;
;             const Src a3 = a2 + kstep, b3 = b2 + kstep;
;             if (last && has_next) H(nxt);
;             if constexpr (SP2) {
;             PG8_TRIP_SP2(PG8_WAIT_V(8));
.LBB0_391:
	s_add_i32 s100, s56, 0xfffc0000
	v_add_u32_e32 v150, 0x10000, v148
	v_add_u32_e32 v151, 0x14000, v148
	ds_read_b128 v[132:135], v150
	ds_read_b128 v[136:139], v150 offset:1024
	ds_read_b128 v[140:143], v150 offset:2048
	ds_read_b128 v[152:155], v150 offset:3072
	ds_read_b128 v[156:159], v151
	ds_read_b128 v[160:163], v151 offset:1024
	ds_read_b128 v[164:167], v151 offset:2048
	ds_read_b128 v[168:171], v151 offset:3072
	s_mov_b32 m0, s41
	s_nop 0
	buffer_load_dwordx4 v144, s[8:11], s100 offen lds
	s_mov_b32 m0, s33
	s_nop 0
	buffer_load_dwordx4 v146, s[8:11], s100 offen lds
	s_mov_b32 m0, s45
	ds_read_b128 v[172:175], v149
	ds_read_b128 v[176:179], v149 offset:1024
	ds_read_b128 v[180:183], v149 offset:2048
	ds_read_b128 v[184:187], v149 offset:3072
	ds_read_b128 v[188:191], v149 offset:4096
	ds_read_b128 v[212:215], v149 offset:5120
	ds_read_b128 v[216:219], v149 offset:6144
	ds_read_b128 v[228:231], v149 offset:7168
	buffer_load_dwordx4 v144, s[8:11], s56 offen lds
	s_mov_b32 m0, s46
	s_nop 0
	buffer_load_dwordx4 v146, s[8:11], s56 offen lds
	s_waitcnt vmcnt(8)
	s_waitcnt lgkmcnt(0)
	s_setprio 1
	s_barrier
	v_mfma_f32_16x16x32_bf16 v[120:123], v[132:135], v[172:175], v[120:123]
	v_mfma_f32_16x16x32_bf16 v[112:115], v[140:143], v[172:175], v[112:115]
	v_mfma_f32_16x16x32_bf16 v[100:103], v[132:135], v[180:183], v[100:103]
	v_mfma_f32_16x16x32_bf16 v[88:91], v[140:143], v[180:183], v[88:91]
	v_mfma_f32_16x16x32_bf16 v[68:71], v[132:135], v[188:191], v[68:71]
	v_mfma_f32_16x16x32_bf16 v[56:59], v[140:143], v[188:191], v[56:59]
	v_mfma_f32_16x16x32_bf16 v[36:39], v[132:135], v[216:219], v[36:39]
	v_mfma_f32_16x16x32_bf16 v[28:31], v[140:143], v[216:219], v[28:31]
	v_mfma_f32_16x16x32_bf16 v[120:123], v[136:139], v[176:179], v[120:123]
	v_mfma_f32_16x16x32_bf16 v[112:115], v[152:155], v[176:179], v[112:115]
	v_mfma_f32_16x16x32_bf16 v[100:103], v[136:139], v[184:187], v[100:103]
	v_mfma_f32_16x16x32_bf16 v[88:91], v[152:155], v[184:187], v[88:91]
	v_mfma_f32_16x16x32_bf16 v[68:71], v[136:139], v[212:215], v[68:71]
	v_mfma_f32_16x16x32_bf16 v[56:59], v[152:155], v[212:215], v[56:59]
	v_mfma_f32_16x16x32_bf16 v[36:39], v[136:139], v[228:231], v[36:39]
	v_mfma_f32_16x16x32_bf16 v[28:31], v[152:155], v[228:231], v[28:31]
	v_mfma_f32_16x16x32_bf16 v[128:131], v[156:159], v[172:175], v[128:131]
	v_mfma_f32_16x16x32_bf16 v[124:127], v[164:167], v[172:175], v[124:127]
	v_mfma_f32_16x16x32_bf16 v[116:119], v[156:159], v[180:183], v[116:119]
	v_mfma_f32_16x16x32_bf16 v[108:111], v[164:167], v[180:183], v[108:111]
	v_mfma_f32_16x16x32_bf16 v[92:95], v[156:159], v[188:191], v[92:95]
	v_mfma_f32_16x16x32_bf16 v[80:83], v[164:167], v[188:191], v[80:83]
	v_mfma_f32_16x16x32_bf16 v[64:67], v[156:159], v[216:219], v[64:67]
	v_mfma_f32_16x16x32_bf16 v[48:51], v[164:167], v[216:219], v[48:51]
	v_mfma_f32_16x16x32_bf16 v[128:131], v[160:163], v[176:179], v[128:131]
	v_mfma_f32_16x16x32_bf16 v[124:127], v[168:171], v[176:179], v[124:127]
	v_mfma_f32_16x16x32_bf16 v[116:119], v[160:163], v[184:187], v[116:119]
	v_mfma_f32_16x16x32_bf16 v[108:111], v[168:171], v[184:187], v[108:111]
	v_mfma_f32_16x16x32_bf16 v[92:95], v[160:163], v[212:215], v[92:95]
	v_mfma_f32_16x16x32_bf16 v[80:83], v[168:171], v[212:215], v[80:83]
	v_mfma_f32_16x16x32_bf16 v[64:67], v[160:163], v[228:231], v[64:67]
	v_mfma_f32_16x16x32_bf16 v[48:51], v[168:171], v[228:231], v[48:51]
	s_barrier
	s_setprio 0
	s_add_i32 s12, s56, 0xfffc0080
	s_cmp_eq_u32 s29, 12
	s_cselect_b32 s60, s68, s12
	s_cselect_b32 s13, s5, s77
	s_cselect_b32 s12, s4, s76
	s_cselect_b32 s15, s7, s55
	s_cselect_b32 s14, s6, s54
	s_cselect_b32 s58, s69, s57
	s_cselect_b32 s16, s0, s8
	s_cselect_b32 s17, s1, s9
	s_cselect_b32 s18, s2, s10
	s_cselect_b32 s19, s3, s11
	s_or_b32 s59, s60, 0x80
	s_mov_b32 m0, s92
	ds_read_b128 v[172:175], v149 offset:16384
	ds_read_b128 v[176:179], v149 offset:17408
	ds_read_b128 v[180:183], v149 offset:18432
	ds_read_b128 v[184:187], v149 offset:19456
	ds_read_b128 v[188:191], v149 offset:20480
	ds_read_b128 v[212:215], v149 offset:21504
	ds_read_b128 v[216:219], v149 offset:22528
	ds_read_b128 v[228:231], v149 offset:23552
	buffer_load_dwordx4 v145, s[12:15], s58 offen lds
	s_mov_b32 m0, s93
	s_add_i32 s61, s58, 0x40000
	buffer_load_dwordx4 v147, s[12:15], s58 offen lds
	s_mov_b32 m0, s94
	s_nop 0
	buffer_load_dwordx4 v145, s[12:15], s61 offen lds
	s_mov_b32 m0, s95
	s_nop 0
	buffer_load_dwordx4 v147, s[12:15], s61 offen lds
	s_waitcnt vmcnt(6)
	s_waitcnt lgkmcnt(0)
	s_setprio 1
	s_barrier
	v_mfma_f32_16x16x32_bf16 v[72:75], v[132:135], v[172:175], v[72:75]
	v_mfma_f32_16x16x32_bf16 v[60:63], v[140:143], v[172:175], v[60:63]
	v_mfma_f32_16x16x32_bf16 v[40:43], v[132:135], v[180:183], v[40:43]
	v_mfma_f32_16x16x32_bf16 v[32:35], v[140:143], v[180:183], v[32:35]
	v_mfma_f32_16x16x32_bf16 v[16:19], v[132:135], v[188:191], v[16:19]
	v_mfma_f32_16x16x32_bf16 v[12:15], v[140:143], v[188:191], v[12:15]
	v_mfma_f32_16x16x32_bf16 v[8:11], v[132:135], v[216:219], v[8:11]
	v_mfma_f32_16x16x32_bf16 v[2:5], v[140:143], v[216:219], v[4:7]
	v_mfma_f32_16x16x32_bf16 v[72:75], v[136:139], v[176:179], v[72:75]
	v_mfma_f32_16x16x32_bf16 v[60:63], v[152:155], v[176:179], v[60:63]
	v_mfma_f32_16x16x32_bf16 v[40:43], v[136:139], v[184:187], v[40:43]
	v_mfma_f32_16x16x32_bf16 v[32:35], v[152:155], v[184:187], v[32:35]
	v_mfma_f32_16x16x32_bf16 v[16:19], v[136:139], v[212:215], v[16:19]
	v_mfma_f32_16x16x32_bf16 v[12:15], v[152:155], v[212:215], v[12:15]
	v_mfma_f32_16x16x32_bf16 v[8:11], v[136:139], v[228:231], v[8:11]
	v_mfma_f32_16x16x32_bf16 v[2:5], v[152:155], v[228:231], v[2:5]
	v_mfma_f32_16x16x32_bf16 v[96:99], v[156:159], v[172:175], v[96:99]
	v_mfma_f32_16x16x32_bf16 v[104:107], v[164:167], v[172:175], v[104:107]
	v_mfma_f32_16x16x32_bf16 v[84:87], v[156:159], v[180:183], v[84:87]
	v_mfma_f32_16x16x32_bf16 v[76:79], v[164:167], v[180:183], v[76:79]
	v_mfma_f32_16x16x32_bf16 v[52:55], v[156:159], v[188:191], v[52:55]
	v_mfma_f32_16x16x32_bf16 v[44:47], v[164:167], v[188:191], v[44:47]
	v_mfma_f32_16x16x32_bf16 v[24:27], v[156:159], v[216:219], v[24:27]
	v_mfma_f32_16x16x32_bf16 v[20:23], v[164:167], v[216:219], v[20:23]
	v_mfma_f32_16x16x32_bf16 v[96:99], v[160:163], v[176:179], v[96:99]
	v_mfma_f32_16x16x32_bf16 v[104:107], v[168:171], v[176:179], v[104:107]
	v_mfma_f32_16x16x32_bf16 v[84:87], v[160:163], v[184:187], v[84:87]
	v_mfma_f32_16x16x32_bf16 v[76:79], v[168:171], v[184:187], v[76:79]
	v_mfma_f32_16x16x32_bf16 v[52:55], v[160:163], v[212:215], v[52:55]
	v_mfma_f32_16x16x32_bf16 v[44:47], v[168:171], v[212:215], v[44:47]
	v_mfma_f32_16x16x32_bf16 v[24:27], v[160:163], v[228:231], v[24:27]
	v_mfma_f32_16x16x32_bf16 v[20:23], v[168:171], v[228:231], v[20:23]
	s_barrier
; #define PG8_WAIT_V(n) asm volatile("s_waitcnt vmcnt(" #n ")" ::: "memory")
; template <class Epi, bool ALIGN_EPI, bool SP2, class Hook>
; __device__ __forceinline__ void gemm_phase(LAS unsigned char* lds, const Gemm g, const StaticOrder& S, const Epi& E, Acc& acc, const bool fresh, const Hook& H, const int wave_id) {
;     ...
;         for (int t = t0; t < nt; t += 2) {
;             const bool last = (t == nt - 2);
;             const Src a1 = cA + (size_t)(t + 1) * kstep;
;             const Src a2 = last ? nA : cA + (size_t)(t + 2) * kstep, b2 = last ? nB : cB + (size_t)(t + 2) * kstep;
;             const Src a3 = a2 + kstep, b3 = b2 + kstep;
;             if (last && has_next) H(nxt);
;             if constexpr (SP2) {
;             PG8_TRIP_SP2(PG8_WAIT_V(8));
	s_setprio 0
	s_mov_b32 m0, s44
	s_nop 0
	buffer_load_dwordx4 v144, s[16:19], s60 offen lds
	s_mov_b32 m0, s36
	s_nop 0
	buffer_load_dwordx4 v146, s[16:19], s60 offen lds
	v_add_u32_e32 v152, 0x18000, v148
	v_add_u32_e32 v153, 0x1c000, v148
	ds_read_b128 v[132:135], v152
	ds_read_b128 v[136:139], v152 offset:1024
	ds_read_b128 v[140:143], v152 offset:2048
	ds_read_b128 v[154:157], v152 offset:3072
	ds_read_b128 v[158:161], v153
	ds_read_b128 v[162:165], v153 offset:1024
	ds_read_b128 v[166:169], v153 offset:2048
	ds_read_b128 v[170:173], v153 offset:3072
	s_add_i32 s60, s60, 0x40000
	s_mov_b32 m0, s37
	ds_read_b128 v[174:177], v149 offset:32768
	ds_read_b128 v[178:181], v149 offset:33792
	ds_read_b128 v[182:185], v149 offset:34816
	ds_read_b128 v[186:189], v149 offset:35840
	ds_read_b128 v[190:193], v149 offset:36864
	ds_read_b128 v[212:215], v149 offset:37888
	ds_read_b128 v[216:219], v149 offset:38912
	ds_read_b128 v[228:231], v149 offset:39936
	buffer_load_dwordx4 v144, s[16:19], s60 offen lds
	s_mov_b32 m0, s38
	s_nop 0
	buffer_load_dwordx4 v146, s[16:19], s60 offen lds
	s_waitcnt vmcnt(8)
	s_waitcnt lgkmcnt(0)
	s_setprio 1
	s_barrier
	v_mfma_f32_16x16x32_bf16 v[120:123], v[132:135], v[174:177], v[120:123]
	v_mfma_f32_16x16x32_bf16 v[112:115], v[140:143], v[174:177], v[112:115]
	v_mfma_f32_16x16x32_bf16 v[100:103], v[132:135], v[182:185], v[100:103]
	v_mfma_f32_16x16x32_bf16 v[88:91], v[140:143], v[182:185], v[88:91]
	v_mfma_f32_16x16x32_bf16 v[68:71], v[132:135], v[190:193], v[68:71]
	v_mfma_f32_16x16x32_bf16 v[56:59], v[140:143], v[190:193], v[56:59]
	v_mfma_f32_16x16x32_bf16 v[36:39], v[132:135], v[216:219], v[36:39]
	v_mfma_f32_16x16x32_bf16 v[28:31], v[140:143], v[216:219], v[28:31]
	v_mfma_f32_16x16x32_bf16 v[120:123], v[136:139], v[178:181], v[120:123]
	v_mfma_f32_16x16x32_bf16 v[112:115], v[154:157], v[178:181], v[112:115]
	v_mfma_f32_16x16x32_bf16 v[100:103], v[136:139], v[186:189], v[100:103]
	v_mfma_f32_16x16x32_bf16 v[88:91], v[154:157], v[186:189], v[88:91]
	v_mfma_f32_16x16x32_bf16 v[68:71], v[136:139], v[212:215], v[68:71]
	v_mfma_f32_16x16x32_bf16 v[56:59], v[154:157], v[212:215], v[56:59]
	v_mfma_f32_16x16x32_bf16 v[36:39], v[136:139], v[228:231], v[36:39]
	v_mfma_f32_16x16x32_bf16 v[28:31], v[154:157], v[228:231], v[28:31]
	v_mfma_f32_16x16x32_bf16 v[128:131], v[158:161], v[174:177], v[128:131]
	v_mfma_f32_16x16x32_bf16 v[124:127], v[166:169], v[174:177], v[124:127]
	v_mfma_f32_16x16x32_bf16 v[116:119], v[158:161], v[182:185], v[116:119]
	v_mfma_f32_16x16x32_bf16 v[108:111], v[166:169], v[182:185], v[108:111]
	v_mfma_f32_16x16x32_bf16 v[92:95], v[158:161], v[190:193], v[92:95]
	v_mfma_f32_16x16x32_bf16 v[80:83], v[166:169], v[190:193], v[80:83]
	v_mfma_f32_16x16x32_bf16 v[64:67], v[158:161], v[216:219], v[64:67]
	v_mfma_f32_16x16x32_bf16 v[48:51], v[166:169], v[216:219], v[48:51]
	v_mfma_f32_16x16x32_bf16 v[128:131], v[162:165], v[178:181], v[128:131]
	v_mfma_f32_16x16x32_bf16 v[124:127], v[170:173], v[178:181], v[124:127]
	v_mfma_f32_16x16x32_bf16 v[116:119], v[162:165], v[186:189], v[116:119]
	v_mfma_f32_16x16x32_bf16 v[108:111], v[170:173], v[186:189], v[108:111]
	v_mfma_f32_16x16x32_bf16 v[92:95], v[162:165], v[212:215], v[92:95]
	v_mfma_f32_16x16x32_bf16 v[80:83], v[170:173], v[212:215], v[80:83]
	v_mfma_f32_16x16x32_bf16 v[64:67], v[162:165], v[228:231], v[64:67]
	v_mfma_f32_16x16x32_bf16 v[48:51], v[170:173], v[228:231], v[48:51]
	s_barrier
	s_setprio 0
	s_mov_b32 m0, s39
	s_or_b32 s60, s58, 0x80
	ds_read_b128 v[174:177], v149 offset:49152
	ds_read_b128 v[178:181], v149 offset:50176
	ds_read_b128 v[182:185], v149 offset:51200
	ds_read_b128 v[186:189], v149 offset:52224
	ds_read_b128 v[190:193], v149 offset:53248
	ds_read_b128 v[212:215], v149 offset:54272
	ds_read_b128 v[216:219], v149 offset:55296
	ds_read_b128 v[228:231], v149 offset:56320
	buffer_load_dwordx4 v145, s[12:15], s60 offen lds
	s_mov_b32 m0, s40
	s_add_i32 s58, s58, 0x40080
	buffer_load_dwordx4 v147, s[12:15], s60 offen lds
	s_mov_b32 m0, s43
	s_nop 0
	buffer_load_dwordx4 v145, s[12:15], s58 offen lds
	s_mov_b32 m0, s42
	s_nop 0
	buffer_load_dwordx4 v147, s[12:15], s58 offen lds
	s_waitcnt vmcnt(6)
	s_waitcnt lgkmcnt(0)
	s_setprio 1
	s_barrier
	v_mfma_f32_16x16x32_bf16 v[72:75], v[132:135], v[174:177], v[72:75]
	v_mfma_f32_16x16x32_bf16 v[60:63], v[140:143], v[174:177], v[60:63]
	v_mfma_f32_16x16x32_bf16 v[40:43], v[132:135], v[182:185], v[40:43]
	v_mfma_f32_16x16x32_bf16 v[32:35], v[140:143], v[182:185], v[32:35]
	v_mfma_f32_16x16x32_bf16 v[16:19], v[132:135], v[190:193], v[16:19]
	v_mfma_f32_16x16x32_bf16 v[12:15], v[140:143], v[190:193], v[12:15]
	v_mfma_f32_16x16x32_bf16 v[6:9], v[132:135], v[216:219], v[8:11]
	v_mfma_f32_16x16x32_bf16 v[2:5], v[140:143], v[216:219], v[2:5]
	v_mfma_f32_16x16x32_bf16 v[72:75], v[136:139], v[178:181], v[72:75]
	v_mfma_f32_16x16x32_bf16 v[60:63], v[154:157], v[178:181], v[60:63]
	v_mfma_f32_16x16x32_bf16 v[40:43], v[136:139], v[186:189], v[40:43]
	v_mfma_f32_16x16x32_bf16 v[32:35], v[154:157], v[186:189], v[32:35]
	v_mfma_f32_16x16x32_bf16 v[16:19], v[136:139], v[212:215], v[16:19]
	v_mfma_f32_16x16x32_bf16 v[12:15], v[154:157], v[212:215], v[12:15]
	v_mfma_f32_16x16x32_bf16 v[8:11], v[136:139], v[228:231], v[6:9]
	v_mfma_f32_16x16x32_bf16 v[4:7], v[154:157], v[228:231], v[2:5]
	v_mfma_f32_16x16x32_bf16 v[96:99], v[158:161], v[174:177], v[96:99]
	v_mfma_f32_16x16x32_bf16 v[104:107], v[166:169], v[174:177], v[104:107]
	v_mfma_f32_16x16x32_bf16 v[84:87], v[158:161], v[182:185], v[84:87]
	v_mfma_f32_16x16x32_bf16 v[76:79], v[166:169], v[182:185], v[76:79]
	v_mfma_f32_16x16x32_bf16 v[52:55], v[158:161], v[190:193], v[52:55]
	v_mfma_f32_16x16x32_bf16 v[44:47], v[166:169], v[190:193], v[44:47]
	v_mfma_f32_16x16x32_bf16 v[24:27], v[158:161], v[216:219], v[24:27]
	v_mfma_f32_16x16x32_bf16 v[20:23], v[166:169], v[216:219], v[20:23]
	v_mfma_f32_16x16x32_bf16 v[96:99], v[162:165], v[178:181], v[96:99]
	v_mfma_f32_16x16x32_bf16 v[104:107], v[170:173], v[178:181], v[104:107]
	v_mfma_f32_16x16x32_bf16 v[84:87], v[162:165], v[186:189], v[84:87]
	v_mfma_f32_16x16x32_bf16 v[76:79], v[170:173], v[186:189], v[76:79]
	v_mfma_f32_16x16x32_bf16 v[52:55], v[162:165], v[212:215], v[52:55]
	v_mfma_f32_16x16x32_bf16 v[44:47], v[170:173], v[212:215], v[44:47]
	v_mfma_f32_16x16x32_bf16 v[24:27], v[162:165], v[228:231], v[24:27]
	v_mfma_f32_16x16x32_bf16 v[20:23], v[170:173], v[228:231], v[20:23]
	s_barrier
	s_setprio 0
	s_add_i32 s29, s29, 2
	s_addk_i32 s56, 0x100
	s_addk_i32 s57, 0x100
	s_cmp_gt_u32 s29, 13
	s_cbranch_scc0 .LBB0_391
	s_mov_b32 m0, s41
	s_nop 0
	buffer_load_dwordx4 v144, s[16:19], s59 offen lds
	s_mov_b32 m0, s33
	s_nop 0
	buffer_load_dwordx4 v146, s[16:19], s59 offen lds
	v_readlane_b32 s8, v251, 45
	v_readlane_b32 s9, v251, 46
	s_and_b64 vcc, exec, s[8:9]
	s_cbranch_vccz .LBB0_394
	s_barrier

; #define PG8_WAIT_V(n) asm volatile("s_waitcnt vmcnt(" #n ")" ::: "memory")
; template <class Epi, bool ALIGN_EPI, bool SP2, class Hook>
; __device__ __forceinline__ void gemm_phase(LAS unsigned char* lds, const Gemm g, const StaticOrder& S, const Epi& E, Acc& acc, const bool fresh, const Hook& H, const int wave_id) {
;     ...
;             const bool last = (t == nt - 2);
;             const Src a1 = cA + (size_t)(t + 1) * kstep;
;             const Src a2 = last ? nA : cA + (size_t)(t + 2) * kstep, b2 = last ? nB : cB + (size_t)(t + 2) * kstep;
;             const Src a3 = a2 + kstep, b3 = b2 + kstep;
;             if (last && has_next) H(nxt);
;             if constexpr (SP2) {
;             PG8_TRIP_SP2(PG8_WAIT_V(8));
.LBB0_903:
	s_add_i32 s100, s55, 0xfffe0000
	v_add_u32_e32 v70, 0x10000, v216
	v_add_u32_e32 v118, 0x14000, v216
	ds_read_b128 v[34:37], v70
	ds_read_b128 v[46:49], v70 offset:1024
	ds_read_b128 v[58:61], v70 offset:2048
	ds_read_b128 v[70:73], v70 offset:3072
	ds_read_b128 v[82:85], v118
	ds_read_b128 v[94:97], v118 offset:1024
	ds_read_b128 v[106:109], v118 offset:2048
	ds_read_b128 v[118:121], v118 offset:3072
	s_mov_b32 m0, s41
	s_nop 0
	buffer_load_dwordx4 v0, s[8:11], s100 offen lds
	s_mov_b32 m0, s33
	s_nop 0
	buffer_load_dwordx4 v214, s[8:11], s100 offen lds
	s_mov_b32 m0, s45
	ds_read_b128 v[130:133], v217
	ds_read_b128 v[142:145], v217 offset:1024
	ds_read_b128 v[154:157], v217 offset:2048
	ds_read_b128 v[166:169], v217 offset:3072
	ds_read_b128 v[174:177], v217 offset:4096
	ds_read_b128 v[182:185], v217 offset:5120
	ds_read_b128 v[186:189], v217 offset:6144
	ds_read_b128 v[190:193], v217 offset:7168
	buffer_load_dwordx4 v0, s[8:11], s55 offen lds
	s_mov_b32 m0, s46
	s_nop 0
	buffer_load_dwordx4 v214, s[8:11], s55 offen lds
	s_waitcnt vmcnt(8)
	s_waitcnt lgkmcnt(0)
	s_setprio 1
	s_barrier
	v_mfma_f32_16x16x32_bf16 v[178:181], v[34:37], v[130:133], v[178:181]
	v_mfma_f32_16x16x32_bf16 v[170:173], v[58:61], v[130:133], v[170:173]
	v_mfma_f32_16x16x32_bf16 v[150:153], v[34:37], v[154:157], v[150:153]
	v_mfma_f32_16x16x32_bf16 v[146:149], v[58:61], v[154:157], v[146:149]
	v_mfma_f32_16x16x32_bf16 v[126:129], v[34:37], v[174:177], v[126:129]
	v_mfma_f32_16x16x32_bf16 v[122:125], v[58:61], v[174:177], v[122:125]
	v_mfma_f32_16x16x32_bf16 v[102:105], v[34:37], v[186:189], v[102:105]
	v_mfma_f32_16x16x32_bf16 v[98:101], v[58:61], v[186:189], v[98:101]
	v_mfma_f32_16x16x32_bf16 v[178:181], v[46:49], v[142:145], v[178:181]
	v_mfma_f32_16x16x32_bf16 v[170:173], v[70:73], v[142:145], v[170:173]
	v_mfma_f32_16x16x32_bf16 v[150:153], v[46:49], v[166:169], v[150:153]
	v_mfma_f32_16x16x32_bf16 v[146:149], v[70:73], v[166:169], v[146:149]
	v_mfma_f32_16x16x32_bf16 v[126:129], v[46:49], v[182:185], v[126:129]
	v_mfma_f32_16x16x32_bf16 v[122:125], v[70:73], v[182:185], v[122:125]
	v_mfma_f32_16x16x32_bf16 v[102:105], v[46:49], v[190:193], v[102:105]
	v_mfma_f32_16x16x32_bf16 v[98:101], v[70:73], v[190:193], v[98:101]
	v_mfma_f32_16x16x32_bf16 v[162:165], v[82:85], v[130:133], v[162:165]
	v_mfma_f32_16x16x32_bf16 v[138:141], v[82:85], v[154:157], v[138:141]
	v_mfma_f32_16x16x32_bf16 v[134:137], v[106:109], v[154:157], v[134:137]
	v_mfma_f32_16x16x32_bf16 v[114:117], v[82:85], v[174:177], v[114:117]
	v_mfma_f32_16x16x32_bf16 v[110:113], v[106:109], v[174:177], v[110:113]
	v_mfma_f32_16x16x32_bf16 v[90:93], v[82:85], v[186:189], v[90:93]
	v_mfma_f32_16x16x32_bf16 v[86:89], v[106:109], v[186:189], v[86:89]
	v_mfma_f32_16x16x32_bf16 v[162:165], v[94:97], v[142:145], v[162:165]
	v_mfma_f32_16x16x32_bf16 v[130:133], v[106:109], v[130:133], v[158:161]
	v_mfma_f32_16x16x32_bf16 v[138:141], v[94:97], v[166:169], v[138:141]
	v_mfma_f32_16x16x32_bf16 v[134:137], v[118:121], v[166:169], v[134:137]
	v_mfma_f32_16x16x32_bf16 v[114:117], v[94:97], v[182:185], v[114:117]
	v_mfma_f32_16x16x32_bf16 v[110:113], v[118:121], v[182:185], v[110:113]
	v_mfma_f32_16x16x32_bf16 v[90:93], v[94:97], v[190:193], v[90:93]
	v_mfma_f32_16x16x32_bf16 v[86:89], v[118:121], v[190:193], v[86:89]
	v_mfma_f32_16x16x32_bf16 v[130:133], v[118:121], v[142:145], v[130:133]
	s_barrier
	s_setprio 0
	s_add_i32 s12, s55, 0xfffe0080
	s_cmp_eq_u32 s57, 4
	s_cselect_b32 s60, s53, s12
	s_cselect_b32 s13, s29, s77
	s_cselect_b32 s12, s28, s76
	s_cselect_b32 s15, s31, s35
	s_cselect_b32 s14, s30, s34
	s_cselect_b32 s58, s54, s56
	s_cselect_b32 s16, s2, s8
	s_cselect_b32 s17, s3, s9
	s_cselect_b32 s18, s26, s10
	s_cselect_b32 s19, s27, s11
	s_or_b32 s59, s60, 0x80
	s_mov_b32 m0, s92
	ds_read_b128 v[142:145], v217 offset:16384
	ds_read_b128 v[154:157], v217 offset:17408
	ds_read_b128 v[158:161], v217 offset:18432
	ds_read_b128 v[166:169], v217 offset:19456
	ds_read_b128 v[174:177], v217 offset:20480
	ds_read_b128 v[182:185], v217 offset:21504
	ds_read_b128 v[186:189], v217 offset:22528
	ds_read_b128 v[190:193], v217 offset:23552
	buffer_load_dwordx4 v199, s[12:15], s58 offen lds
	s_mov_b32 m0, s93
	s_add_i32 s61, s58, 0x20000
	buffer_load_dwordx4 v215, s[12:15], s58 offen lds
	s_mov_b32 m0, s94
	s_nop 0
	buffer_load_dwordx4 v199, s[12:15], s61 offen lds
	s_mov_b32 m0, s95
	s_nop 0
	buffer_load_dwordx4 v215, s[12:15], s61 offen lds
	s_waitcnt vmcnt(6)
	s_waitcnt lgkmcnt(0)
	s_setprio 1
	s_barrier
	v_mfma_f32_16x16x32_bf16 v[78:81], v[34:37], v[142:145], v[78:81]
	v_mfma_f32_16x16x32_bf16 v[74:77], v[58:61], v[142:145], v[74:77]
	v_mfma_f32_16x16x32_bf16 v[54:57], v[34:37], v[158:161], v[54:57]
	v_mfma_f32_16x16x32_bf16 v[50:53], v[58:61], v[158:161], v[50:53]
	v_mfma_f32_16x16x32_bf16 v[30:33], v[34:37], v[174:177], v[30:33]
	v_mfma_f32_16x16x32_bf16 v[26:29], v[58:61], v[174:177], v[26:29]
	v_mfma_f32_16x16x32_bf16 v[14:17], v[34:37], v[186:189], v[14:17]
	v_mfma_f32_16x16x32_bf16 v[10:13], v[58:61], v[186:189], v[10:13]
	v_mfma_f32_16x16x32_bf16 v[78:81], v[46:49], v[154:157], v[78:81]
	v_mfma_f32_16x16x32_bf16 v[74:77], v[70:73], v[154:157], v[74:77]
	v_mfma_f32_16x16x32_bf16 v[54:57], v[46:49], v[166:169], v[54:57]
	v_mfma_f32_16x16x32_bf16 v[50:53], v[70:73], v[166:169], v[50:53]
	v_mfma_f32_16x16x32_bf16 v[30:33], v[46:49], v[182:185], v[30:33]
	v_mfma_f32_16x16x32_bf16 v[26:29], v[70:73], v[182:185], v[26:29]
	v_mfma_f32_16x16x32_bf16 v[14:17], v[46:49], v[190:193], v[14:17]
	v_mfma_f32_16x16x32_bf16 v[10:13], v[70:73], v[190:193], v[10:13]
	v_mfma_f32_16x16x32_bf16 v[42:45], v[82:85], v[158:161], v[42:45]
	v_mfma_f32_16x16x32_bf16 v[38:41], v[106:109], v[158:161], v[38:41]
	v_mfma_f32_16x16x32_bf16 v[22:25], v[82:85], v[174:177], v[22:25]
	v_mfma_f32_16x16x32_bf16 v[18:21], v[106:109], v[174:177], v[18:21]
	v_mfma_f32_16x16x32_bf16 v[6:9], v[82:85], v[186:189], v[6:9]
	v_mfma_f32_16x16x32_bf16 v[2:5], v[106:109], v[186:189], v[2:5]
	v_mfma_f32_16x16x32_bf16 v[34:37], v[82:85], v[142:145], v[66:69]
	v_mfma_f32_16x16x32_bf16 v[46:49], v[106:109], v[142:145], v[62:65]
	v_mfma_f32_16x16x32_bf16 v[42:45], v[94:97], v[166:169], v[42:45]
	v_mfma_f32_16x16x32_bf16 v[38:41], v[118:121], v[166:169], v[38:41]
	v_mfma_f32_16x16x32_bf16 v[22:25], v[94:97], v[182:185], v[22:25]
	v_mfma_f32_16x16x32_bf16 v[18:21], v[118:121], v[182:185], v[18:21]
	v_mfma_f32_16x16x32_bf16 v[6:9], v[94:97], v[190:193], v[6:9]
	v_mfma_f32_16x16x32_bf16 v[2:5], v[118:121], v[190:193], v[2:5]
	v_mfma_f32_16x16x32_bf16 v[34:37], v[94:97], v[154:157], v[34:37]
	v_mfma_f32_16x16x32_bf16 v[46:49], v[118:121], v[154:157], v[46:49]
	s_barrier
; #define PG8_WAIT_V(n) asm volatile("s_waitcnt vmcnt(" #n ")" ::: "memory")
; template <class Epi, bool ALIGN_EPI, bool SP2, class Hook>
; __device__ __forceinline__ void gemm_phase(LAS unsigned char* lds, const Gemm g, const StaticOrder& S, const Epi& E, Acc& acc, const bool fresh, const Hook& H, const int wave_id) {
;     ...
;         for (int t = t0; t < nt; t += 2) {
;             const bool last = (t == nt - 2);
;             const Src a1 = cA + (size_t)(t + 1) * kstep;
;             const Src a2 = last ? nA : cA + (size_t)(t + 2) * kstep, b2 = last ? nB : cB + (size_t)(t + 2) * kstep;
;             const Src a3 = a2 + kstep, b3 = b2 + kstep;
;             if (last && has_next) H(nxt);
;             if constexpr (SP2) {
;             PG8_TRIP_SP2(PG8_WAIT_V(8));
	s_setprio 0
	s_mov_b32 m0, s44
	s_nop 0
	buffer_load_dwordx4 v0, s[16:19], s60 offen lds
	s_mov_b32 m0, s36
	s_nop 0
	buffer_load_dwordx4 v214, s[16:19], s60 offen lds
	v_add_u32_e32 v70, 0x18000, v216
	v_add_u32_e32 v118, 0x1c000, v216
	ds_read_b128 v[58:61], v70
	ds_read_b128 v[62:65], v70 offset:1024
	ds_read_b128 v[66:69], v70 offset:2048
	ds_read_b128 v[70:73], v70 offset:3072
	ds_read_b128 v[82:85], v118
	ds_read_b128 v[94:97], v118 offset:1024
	ds_read_b128 v[106:109], v118 offset:2048
	ds_read_b128 v[118:121], v118 offset:3072
	s_add_i32 s60, s60, 0x20000
	s_mov_b32 m0, s37
	ds_read_b128 v[142:145], v217 offset:32768
	ds_read_b128 v[154:157], v217 offset:33792
	ds_read_b128 v[166:169], v217 offset:34816
	ds_read_b128 v[174:177], v217 offset:35840
	ds_read_b128 v[182:185], v217 offset:36864
	ds_read_b128 v[186:189], v217 offset:37888
	ds_read_b128 v[190:193], v217 offset:38912
	ds_read_b128 v[194:197], v217 offset:39936
	buffer_load_dwordx4 v0, s[16:19], s60 offen lds
	s_mov_b32 m0, s38
	s_nop 0
	buffer_load_dwordx4 v214, s[16:19], s60 offen lds
	s_waitcnt vmcnt(8)
	s_waitcnt lgkmcnt(0)
	s_setprio 1
	s_barrier
	v_mfma_f32_16x16x32_bf16 v[158:161], v[58:61], v[142:145], v[178:181]
	v_mfma_f32_16x16x32_bf16 v[178:181], v[62:65], v[154:157], v[158:161]
	v_mfma_f32_16x16x32_bf16 v[158:161], v[66:69], v[142:145], v[170:173]
	v_mfma_f32_16x16x32_bf16 v[150:153], v[58:61], v[166:169], v[150:153]
	v_mfma_f32_16x16x32_bf16 v[146:149], v[66:69], v[166:169], v[146:149]
	v_mfma_f32_16x16x32_bf16 v[126:129], v[58:61], v[182:185], v[126:129]
	v_mfma_f32_16x16x32_bf16 v[122:125], v[66:69], v[182:185], v[122:125]
	v_mfma_f32_16x16x32_bf16 v[102:105], v[58:61], v[190:193], v[102:105]
	v_mfma_f32_16x16x32_bf16 v[98:101], v[66:69], v[190:193], v[98:101]
	v_mfma_f32_16x16x32_bf16 v[170:173], v[70:73], v[154:157], v[158:161]
	v_mfma_f32_16x16x32_bf16 v[150:153], v[62:65], v[174:177], v[150:153]
	v_mfma_f32_16x16x32_bf16 v[146:149], v[70:73], v[174:177], v[146:149]
	v_mfma_f32_16x16x32_bf16 v[126:129], v[62:65], v[186:189], v[126:129]
	v_mfma_f32_16x16x32_bf16 v[122:125], v[70:73], v[186:189], v[122:125]
	v_mfma_f32_16x16x32_bf16 v[102:105], v[62:65], v[194:197], v[102:105]
	v_mfma_f32_16x16x32_bf16 v[98:101], v[70:73], v[194:197], v[98:101]
	v_mfma_f32_16x16x32_bf16 v[158:161], v[82:85], v[142:145], v[162:165]
	v_mfma_f32_16x16x32_bf16 v[130:133], v[106:109], v[142:145], v[130:133]
	v_mfma_f32_16x16x32_bf16 v[162:165], v[94:97], v[154:157], v[158:161]
	v_mfma_f32_16x16x32_bf16 v[158:161], v[118:121], v[154:157], v[130:133]
	v_mfma_f32_16x16x32_bf16 v[130:133], v[82:85], v[166:169], v[138:141]
	v_mfma_f32_16x16x32_bf16 v[138:141], v[94:97], v[174:177], v[130:133]
	v_mfma_f32_16x16x32_bf16 v[130:133], v[106:109], v[166:169], v[134:137]
	v_mfma_f32_16x16x32_bf16 v[114:117], v[82:85], v[182:185], v[114:117]
	v_mfma_f32_16x16x32_bf16 v[110:113], v[106:109], v[182:185], v[110:113]
	v_mfma_f32_16x16x32_bf16 v[90:93], v[82:85], v[190:193], v[90:93]
	v_mfma_f32_16x16x32_bf16 v[86:89], v[106:109], v[190:193], v[86:89]
	v_mfma_f32_16x16x32_bf16 v[134:137], v[118:121], v[174:177], v[130:133]
	v_mfma_f32_16x16x32_bf16 v[114:117], v[94:97], v[186:189], v[114:117]
	v_mfma_f32_16x16x32_bf16 v[110:113], v[118:121], v[186:189], v[110:113]
	v_mfma_f32_16x16x32_bf16 v[90:93], v[94:97], v[194:197], v[90:93]
	v_mfma_f32_16x16x32_bf16 v[86:89], v[118:121], v[194:197], v[86:89]
	s_barrier
	s_setprio 0
	s_mov_b32 m0, s39
	s_or_b32 s60, s58, 0x80
	ds_read_b128 v[130:133], v217 offset:49152
	ds_read_b128 v[142:145], v217 offset:50176
	ds_read_b128 v[154:157], v217 offset:51200
	ds_read_b128 v[166:169], v217 offset:52224
	ds_read_b128 v[174:177], v217 offset:53248
	ds_read_b128 v[182:185], v217 offset:54272
	ds_read_b128 v[186:189], v217 offset:55296
	ds_read_b128 v[190:193], v217 offset:56320
	buffer_load_dwordx4 v199, s[12:15], s60 offen lds
	s_mov_b32 m0, s40
	s_add_i32 s58, s58, 0x20080
	buffer_load_dwordx4 v215, s[12:15], s60 offen lds
	s_mov_b32 m0, s43
	s_nop 0
	buffer_load_dwordx4 v199, s[12:15], s58 offen lds
	s_mov_b32 m0, s42
	s_nop 0
	buffer_load_dwordx4 v215, s[12:15], s58 offen lds
	s_waitcnt vmcnt(6)
	s_waitcnt lgkmcnt(0)
	s_setprio 1
	s_barrier
	v_mfma_f32_16x16x32_bf16 v[78:81], v[58:61], v[130:133], v[78:81]
	v_mfma_f32_16x16x32_bf16 v[74:77], v[66:69], v[130:133], v[74:77]
	v_mfma_f32_16x16x32_bf16 v[54:57], v[58:61], v[154:157], v[54:57]
	v_mfma_f32_16x16x32_bf16 v[50:53], v[66:69], v[154:157], v[50:53]
	v_mfma_f32_16x16x32_bf16 v[30:33], v[58:61], v[174:177], v[30:33]
	v_mfma_f32_16x16x32_bf16 v[26:29], v[66:69], v[174:177], v[26:29]
	v_mfma_f32_16x16x32_bf16 v[14:17], v[58:61], v[186:189], v[14:17]
	v_mfma_f32_16x16x32_bf16 v[10:13], v[66:69], v[186:189], v[10:13]
	v_mfma_f32_16x16x32_bf16 v[78:81], v[62:65], v[142:145], v[78:81]
	v_mfma_f32_16x16x32_bf16 v[74:77], v[70:73], v[142:145], v[74:77]
	v_mfma_f32_16x16x32_bf16 v[54:57], v[62:65], v[166:169], v[54:57]
	v_mfma_f32_16x16x32_bf16 v[50:53], v[70:73], v[166:169], v[50:53]
	v_mfma_f32_16x16x32_bf16 v[30:33], v[62:65], v[182:185], v[30:33]
	v_mfma_f32_16x16x32_bf16 v[26:29], v[70:73], v[182:185], v[26:29]
	v_mfma_f32_16x16x32_bf16 v[14:17], v[62:65], v[190:193], v[14:17]
	v_mfma_f32_16x16x32_bf16 v[10:13], v[70:73], v[190:193], v[10:13]
	v_mfma_f32_16x16x32_bf16 v[34:37], v[82:85], v[130:133], v[34:37]
	v_mfma_f32_16x16x32_bf16 v[66:69], v[94:97], v[142:145], v[34:37]
	v_mfma_f32_16x16x32_bf16 v[34:37], v[106:109], v[130:133], v[46:49]
	v_mfma_f32_16x16x32_bf16 v[62:65], v[118:121], v[142:145], v[34:37]
	v_mfma_f32_16x16x32_bf16 v[34:37], v[82:85], v[154:157], v[42:45]
	v_mfma_f32_16x16x32_bf16 v[42:45], v[94:97], v[166:169], v[34:37]
	v_mfma_f32_16x16x32_bf16 v[34:37], v[106:109], v[154:157], v[38:41]
	v_mfma_f32_16x16x32_bf16 v[22:25], v[82:85], v[174:177], v[22:25]
	v_mfma_f32_16x16x32_bf16 v[18:21], v[106:109], v[174:177], v[18:21]
	v_mfma_f32_16x16x32_bf16 v[6:9], v[82:85], v[186:189], v[6:9]
	v_mfma_f32_16x16x32_bf16 v[2:5], v[106:109], v[186:189], v[2:5]
	v_mfma_f32_16x16x32_bf16 v[38:41], v[118:121], v[166:169], v[34:37]
	v_mfma_f32_16x16x32_bf16 v[22:25], v[94:97], v[182:185], v[22:25]
	v_mfma_f32_16x16x32_bf16 v[18:21], v[118:121], v[182:185], v[18:21]
	v_mfma_f32_16x16x32_bf16 v[6:9], v[94:97], v[190:193], v[6:9]
	v_mfma_f32_16x16x32_bf16 v[2:5], v[118:121], v[190:193], v[2:5]
	s_barrier
	s_setprio 0
	s_add_i32 s57, s57, 2
	s_addk_i32 s55, 0x100
	s_addk_i32 s56, 0x100
	s_cmp_gt_u32 s57, 5
	s_cbranch_scc0 .LBB0_903
	s_mov_b32 m0, s41
	s_nop 0
	buffer_load_dwordx4 v0, s[16:19], s59 offen lds
	s_mov_b32 m0, s33
	s_nop 0
	buffer_load_dwordx4 v214, s[16:19], s59 offen lds
	v_readlane_b32 s8, v251, 45
	v_readlane_b32 s9, v251, 46
	s_and_b64 vcc, exec, s[8:9]
	s_cbranch_vccz .LBB0_906
	s_barrier

; #define PG8_WAIT_V(n) asm volatile("s_waitcnt vmcnt(" #n ")" ::: "memory")
; template <class Epi, bool ALIGN_EPI, bool SP2, class Hook>
; __device__ __forceinline__ void gemm_phase(LAS unsigned char* lds, const Gemm g, const StaticOrder& S, const Epi& E, Acc& acc, const bool fresh, const Hook& H, const int wave_id) {
;     ...
;             const bool last = (t == nt - 2);
;             const Src a1 = cA + (size_t)(t + 1) * kstep;
;             const Src a2 = last ? nA : cA + (size_t)(t + 2) * kstep, b2 = last ? nB : cB + (size_t)(t + 2) * kstep;
;             const Src a3 = a2 + kstep, b3 = b2 + kstep;
;             if (last && has_next) H(nxt);
;             if constexpr (SP2) {
;             PG8_TRIP_SP2(PG8_WAIT_V(8));
.LBB0_1235:
	s_add_i32 s100, s2, 0xfffc0000
	v_add_u32_e32 v142, 0x10000, v161
	v_add_u32_e32 v163, 0x14000, v161
	ds_read_b128 v[130:133], v142
	ds_read_b128 v[134:137], v142 offset:1024
	ds_read_b128 v[138:141], v142 offset:2048
	ds_read_b128 v[142:145], v142 offset:3072
	ds_read_b128 v[146:149], v163
	ds_read_b128 v[150:153], v163 offset:1024
	ds_read_b128 v[154:157], v163 offset:2048
	ds_read_b128 v[164:167], v163 offset:3072
	s_mov_b32 m0, s41
	s_nop 0
	buffer_load_dwordx4 v0, s[12:15], s100 offen lds
	s_mov_b32 m0, s33
	s_nop 0
	buffer_load_dwordx4 v159, s[12:15], s100 offen lds
	s_mov_b32 m0, s45
	ds_read_b128 v[168:171], v162
	ds_read_b128 v[172:175], v162 offset:1024
	ds_read_b128 v[176:179], v162 offset:2048
	ds_read_b128 v[180:183], v162 offset:3072
	ds_read_b128 v[184:187], v162 offset:4096
	ds_read_b128 v[188:191], v162 offset:5120
	ds_read_b128 v[192:195], v162 offset:6144
	ds_read_b128 v[200:203], v162 offset:7168
	buffer_load_dwordx4 v0, s[12:15], s2 offen lds
	s_mov_b32 m0, s46
	s_nop 0
	buffer_load_dwordx4 v159, s[12:15], s2 offen lds
	s_waitcnt vmcnt(8)
	s_waitcnt lgkmcnt(0)
	s_setprio 1
	s_barrier
	v_mfma_f32_16x16x32_bf16 v[126:129], v[130:133], v[168:171], v[126:129]
	v_mfma_f32_16x16x32_bf16 v[122:125], v[138:141], v[168:171], v[122:125]
	v_mfma_f32_16x16x32_bf16 v[110:113], v[130:133], v[176:179], v[110:113]
	v_mfma_f32_16x16x32_bf16 v[106:109], v[138:141], v[176:179], v[106:109]
	v_mfma_f32_16x16x32_bf16 v[94:97], v[130:133], v[184:187], v[94:97]
	v_mfma_f32_16x16x32_bf16 v[90:93], v[138:141], v[184:187], v[90:93]
	v_mfma_f32_16x16x32_bf16 v[78:81], v[130:133], v[192:195], v[78:81]
	v_mfma_f32_16x16x32_bf16 v[74:77], v[138:141], v[192:195], v[74:77]
	v_mfma_f32_16x16x32_bf16 v[126:129], v[134:137], v[172:175], v[126:129]
	v_mfma_f32_16x16x32_bf16 v[122:125], v[142:145], v[172:175], v[122:125]
	v_mfma_f32_16x16x32_bf16 v[110:113], v[134:137], v[180:183], v[110:113]
	v_mfma_f32_16x16x32_bf16 v[106:109], v[142:145], v[180:183], v[106:109]
	v_mfma_f32_16x16x32_bf16 v[94:97], v[134:137], v[188:191], v[94:97]
	v_mfma_f32_16x16x32_bf16 v[90:93], v[142:145], v[188:191], v[90:93]
	v_mfma_f32_16x16x32_bf16 v[78:81], v[134:137], v[200:203], v[78:81]
	v_mfma_f32_16x16x32_bf16 v[74:77], v[142:145], v[200:203], v[74:77]
	v_mfma_f32_16x16x32_bf16 v[118:121], v[146:149], v[168:171], v[118:121]
	v_mfma_f32_16x16x32_bf16 v[114:117], v[154:157], v[168:171], v[114:117]
	v_mfma_f32_16x16x32_bf16 v[102:105], v[146:149], v[176:179], v[102:105]
	v_mfma_f32_16x16x32_bf16 v[98:101], v[154:157], v[176:179], v[98:101]
	v_mfma_f32_16x16x32_bf16 v[86:89], v[146:149], v[184:187], v[86:89]
	v_mfma_f32_16x16x32_bf16 v[82:85], v[154:157], v[184:187], v[82:85]
	v_mfma_f32_16x16x32_bf16 v[70:73], v[146:149], v[192:195], v[70:73]
	v_mfma_f32_16x16x32_bf16 v[66:69], v[154:157], v[192:195], v[66:69]
	v_mfma_f32_16x16x32_bf16 v[118:121], v[150:153], v[172:175], v[118:121]
	v_mfma_f32_16x16x32_bf16 v[114:117], v[164:167], v[172:175], v[114:117]
	v_mfma_f32_16x16x32_bf16 v[102:105], v[150:153], v[180:183], v[102:105]
	v_mfma_f32_16x16x32_bf16 v[98:101], v[164:167], v[180:183], v[98:101]
	v_mfma_f32_16x16x32_bf16 v[86:89], v[150:153], v[188:191], v[86:89]
	v_mfma_f32_16x16x32_bf16 v[82:85], v[164:167], v[188:191], v[82:85]
	v_mfma_f32_16x16x32_bf16 v[70:73], v[150:153], v[200:203], v[70:73]
	v_mfma_f32_16x16x32_bf16 v[66:69], v[164:167], v[200:203], v[66:69]
	s_barrier
	s_setprio 0
	s_add_i32 s16, s2, 0xfffc0080
	s_cmp_eq_u32 s59, 12
	s_cselect_b32 s62, s55, s16
	s_cselect_b32 s17, s31, s9
	s_cselect_b32 s16, s30, s8
	s_cselect_b32 s19, s35, s51
	s_cselect_b32 s18, s34, s50
	s_cselect_b32 s60, s56, s3
	s_cselect_b32 s20, s26, s12
	s_cselect_b32 s21, s27, s13
	s_cselect_b32 s22, s28, s14
	s_cselect_b32 s23, s29, s15
	s_or_b32 s61, s62, 0x80
	s_mov_b32 m0, s92
	ds_read_b128 v[168:171], v162 offset:16384
	ds_read_b128 v[172:175], v162 offset:17408
	ds_read_b128 v[176:179], v162 offset:18432
	ds_read_b128 v[180:183], v162 offset:19456
	ds_read_b128 v[184:187], v162 offset:20480
	ds_read_b128 v[188:191], v162 offset:21504
	ds_read_b128 v[192:195], v162 offset:22528
	ds_read_b128 v[200:203], v162 offset:23552
	buffer_load_dwordx4 v158, s[16:19], s60 offen lds
	s_mov_b32 m0, s93
	s_add_i32 s63, s60, 0x40000
	buffer_load_dwordx4 v160, s[16:19], s60 offen lds
	s_mov_b32 m0, s94
	s_nop 0
	buffer_load_dwordx4 v158, s[16:19], s63 offen lds
	s_mov_b32 m0, s95
	s_nop 0
	buffer_load_dwordx4 v160, s[16:19], s63 offen lds
	s_waitcnt vmcnt(6)
	s_waitcnt lgkmcnt(0)
	s_setprio 1
	s_barrier
	v_mfma_f32_16x16x32_bf16 v[62:65], v[130:133], v[168:171], v[62:65]
	v_mfma_f32_16x16x32_bf16 v[58:61], v[138:141], v[168:171], v[58:61]
	v_mfma_f32_16x16x32_bf16 v[46:49], v[130:133], v[176:179], v[46:49]
	v_mfma_f32_16x16x32_bf16 v[42:45], v[138:141], v[176:179], v[42:45]
	v_mfma_f32_16x16x32_bf16 v[30:33], v[130:133], v[184:187], v[30:33]
	v_mfma_f32_16x16x32_bf16 v[26:29], v[138:141], v[184:187], v[26:29]
	v_mfma_f32_16x16x32_bf16 v[14:17], v[130:133], v[192:195], v[14:17]
	v_mfma_f32_16x16x32_bf16 v[10:13], v[138:141], v[192:195], v[10:13]
	v_mfma_f32_16x16x32_bf16 v[62:65], v[134:137], v[172:175], v[62:65]
	v_mfma_f32_16x16x32_bf16 v[58:61], v[142:145], v[172:175], v[58:61]
	v_mfma_f32_16x16x32_bf16 v[46:49], v[134:137], v[180:183], v[46:49]
	v_mfma_f32_16x16x32_bf16 v[42:45], v[142:145], v[180:183], v[42:45]
	v_mfma_f32_16x16x32_bf16 v[30:33], v[134:137], v[188:191], v[30:33]
	v_mfma_f32_16x16x32_bf16 v[26:29], v[142:145], v[188:191], v[26:29]
	v_mfma_f32_16x16x32_bf16 v[14:17], v[134:137], v[200:203], v[14:17]
	v_mfma_f32_16x16x32_bf16 v[10:13], v[142:145], v[200:203], v[10:13]
	v_mfma_f32_16x16x32_bf16 v[54:57], v[146:149], v[168:171], v[54:57]
	v_mfma_f32_16x16x32_bf16 v[50:53], v[154:157], v[168:171], v[50:53]
	v_mfma_f32_16x16x32_bf16 v[38:41], v[146:149], v[176:179], v[38:41]
	v_mfma_f32_16x16x32_bf16 v[34:37], v[154:157], v[176:179], v[34:37]
	v_mfma_f32_16x16x32_bf16 v[22:25], v[146:149], v[184:187], v[22:25]
	v_mfma_f32_16x16x32_bf16 v[18:21], v[154:157], v[184:187], v[18:21]
	v_mfma_f32_16x16x32_bf16 v[6:9], v[146:149], v[192:195], v[6:9]
	v_mfma_f32_16x16x32_bf16 v[2:5], v[154:157], v[192:195], v[2:5]
	v_mfma_f32_16x16x32_bf16 v[54:57], v[150:153], v[172:175], v[54:57]
	v_mfma_f32_16x16x32_bf16 v[50:53], v[164:167], v[172:175], v[50:53]
	v_mfma_f32_16x16x32_bf16 v[38:41], v[150:153], v[180:183], v[38:41]
	v_mfma_f32_16x16x32_bf16 v[34:37], v[164:167], v[180:183], v[34:37]
	v_mfma_f32_16x16x32_bf16 v[22:25], v[150:153], v[188:191], v[22:25]
	v_mfma_f32_16x16x32_bf16 v[18:21], v[164:167], v[188:191], v[18:21]
	v_mfma_f32_16x16x32_bf16 v[6:9], v[150:153], v[200:203], v[6:9]
	v_mfma_f32_16x16x32_bf16 v[2:5], v[164:167], v[200:203], v[2:5]
	s_barrier
; #define PG8_WAIT_V(n) asm volatile("s_waitcnt vmcnt(" #n ")" ::: "memory")
; template <class Epi, bool ALIGN_EPI, bool SP2, class Hook>
; __device__ __forceinline__ void gemm_phase(LAS unsigned char* lds, const Gemm g, const StaticOrder& S, const Epi& E, Acc& acc, const bool fresh, const Hook& H, const int wave_id) {
;     ...
;         for (int t = t0; t < nt; t += 2) {
;             const bool last = (t == nt - 2);
;             const Src a1 = cA + (size_t)(t + 1) * kstep;
;             const Src a2 = last ? nA : cA + (size_t)(t + 2) * kstep, b2 = last ? nB : cB + (size_t)(t + 2) * kstep;
;             const Src a3 = a2 + kstep, b3 = b2 + kstep;
;             if (last && has_next) H(nxt);
;             if constexpr (SP2) {
;             PG8_TRIP_SP2(PG8_WAIT_V(8));
	s_setprio 0
	s_mov_b32 m0, s44
	s_nop 0
	buffer_load_dwordx4 v0, s[20:23], s62 offen lds
	s_mov_b32 m0, s36
	s_nop 0
	buffer_load_dwordx4 v159, s[20:23], s62 offen lds
	v_add_u32_e32 v142, 0x18000, v161
	v_add_u32_e32 v163, 0x1c000, v161
	ds_read_b128 v[130:133], v142
	ds_read_b128 v[134:137], v142 offset:1024
	ds_read_b128 v[138:141], v142 offset:2048
	ds_read_b128 v[142:145], v142 offset:3072
	ds_read_b128 v[146:149], v163
	ds_read_b128 v[150:153], v163 offset:1024
	ds_read_b128 v[154:157], v163 offset:2048
	ds_read_b128 v[164:167], v163 offset:3072
	s_add_i32 s62, s62, 0x40000
	s_mov_b32 m0, s37
	ds_read_b128 v[168:171], v162 offset:32768
	ds_read_b128 v[172:175], v162 offset:33792
	ds_read_b128 v[176:179], v162 offset:34816
	ds_read_b128 v[180:183], v162 offset:35840
	ds_read_b128 v[184:187], v162 offset:36864
	ds_read_b128 v[188:191], v162 offset:37888
	ds_read_b128 v[192:195], v162 offset:38912
	ds_read_b128 v[200:203], v162 offset:39936
	buffer_load_dwordx4 v0, s[20:23], s62 offen lds
	s_mov_b32 m0, s38
	s_nop 0
	buffer_load_dwordx4 v159, s[20:23], s62 offen lds
	s_waitcnt vmcnt(8)
	s_waitcnt lgkmcnt(0)
	s_setprio 1
	s_barrier
	v_mfma_f32_16x16x32_bf16 v[126:129], v[130:133], v[168:171], v[126:129]
	v_mfma_f32_16x16x32_bf16 v[122:125], v[138:141], v[168:171], v[122:125]
	v_mfma_f32_16x16x32_bf16 v[110:113], v[130:133], v[176:179], v[110:113]
	v_mfma_f32_16x16x32_bf16 v[106:109], v[138:141], v[176:179], v[106:109]
	v_mfma_f32_16x16x32_bf16 v[94:97], v[130:133], v[184:187], v[94:97]
	v_mfma_f32_16x16x32_bf16 v[90:93], v[138:141], v[184:187], v[90:93]
	v_mfma_f32_16x16x32_bf16 v[78:81], v[130:133], v[192:195], v[78:81]
	v_mfma_f32_16x16x32_bf16 v[74:77], v[138:141], v[192:195], v[74:77]
	v_mfma_f32_16x16x32_bf16 v[126:129], v[134:137], v[172:175], v[126:129]
	v_mfma_f32_16x16x32_bf16 v[122:125], v[142:145], v[172:175], v[122:125]
	v_mfma_f32_16x16x32_bf16 v[110:113], v[134:137], v[180:183], v[110:113]
	v_mfma_f32_16x16x32_bf16 v[106:109], v[142:145], v[180:183], v[106:109]
	v_mfma_f32_16x16x32_bf16 v[94:97], v[134:137], v[188:191], v[94:97]
	v_mfma_f32_16x16x32_bf16 v[90:93], v[142:145], v[188:191], v[90:93]
	v_mfma_f32_16x16x32_bf16 v[78:81], v[134:137], v[200:203], v[78:81]
	v_mfma_f32_16x16x32_bf16 v[74:77], v[142:145], v[200:203], v[74:77]
	v_mfma_f32_16x16x32_bf16 v[118:121], v[146:149], v[168:171], v[118:121]
	v_mfma_f32_16x16x32_bf16 v[114:117], v[154:157], v[168:171], v[114:117]
	v_mfma_f32_16x16x32_bf16 v[102:105], v[146:149], v[176:179], v[102:105]
	v_mfma_f32_16x16x32_bf16 v[98:101], v[154:157], v[176:179], v[98:101]
	v_mfma_f32_16x16x32_bf16 v[86:89], v[146:149], v[184:187], v[86:89]
	v_mfma_f32_16x16x32_bf16 v[82:85], v[154:157], v[184:187], v[82:85]
	v_mfma_f32_16x16x32_bf16 v[70:73], v[146:149], v[192:195], v[70:73]
	v_mfma_f32_16x16x32_bf16 v[66:69], v[154:157], v[192:195], v[66:69]
	v_mfma_f32_16x16x32_bf16 v[118:121], v[150:153], v[172:175], v[118:121]
	v_mfma_f32_16x16x32_bf16 v[114:117], v[164:167], v[172:175], v[114:117]
	v_mfma_f32_16x16x32_bf16 v[102:105], v[150:153], v[180:183], v[102:105]
	v_mfma_f32_16x16x32_bf16 v[98:101], v[164:167], v[180:183], v[98:101]
	v_mfma_f32_16x16x32_bf16 v[86:89], v[150:153], v[188:191], v[86:89]
	v_mfma_f32_16x16x32_bf16 v[82:85], v[164:167], v[188:191], v[82:85]
	v_mfma_f32_16x16x32_bf16 v[70:73], v[150:153], v[200:203], v[70:73]
	v_mfma_f32_16x16x32_bf16 v[66:69], v[164:167], v[200:203], v[66:69]
	s_barrier
	s_setprio 0
	s_mov_b32 m0, s39
	s_or_b32 s62, s60, 0x80
	ds_read_b128 v[168:171], v162 offset:49152
	ds_read_b128 v[172:175], v162 offset:50176
	ds_read_b128 v[176:179], v162 offset:51200
	ds_read_b128 v[180:183], v162 offset:52224
	ds_read_b128 v[184:187], v162 offset:53248
	ds_read_b128 v[188:191], v162 offset:54272
	ds_read_b128 v[192:195], v162 offset:55296
	ds_read_b128 v[200:203], v162 offset:56320
	buffer_load_dwordx4 v158, s[16:19], s62 offen lds
	s_mov_b32 m0, s40
	s_add_i32 s60, s60, 0x40080
	buffer_load_dwordx4 v160, s[16:19], s62 offen lds
	s_mov_b32 m0, s43
	s_nop 0
	buffer_load_dwordx4 v158, s[16:19], s60 offen lds
	s_mov_b32 m0, s42
	s_nop 0
	buffer_load_dwordx4 v160, s[16:19], s60 offen lds
	s_waitcnt vmcnt(6)
	s_waitcnt lgkmcnt(0)
	s_setprio 1
	s_barrier
	v_mfma_f32_16x16x32_bf16 v[62:65], v[130:133], v[168:171], v[62:65]
	v_mfma_f32_16x16x32_bf16 v[58:61], v[138:141], v[168:171], v[58:61]
	v_mfma_f32_16x16x32_bf16 v[46:49], v[130:133], v[176:179], v[46:49]
	v_mfma_f32_16x16x32_bf16 v[42:45], v[138:141], v[176:179], v[42:45]
	v_mfma_f32_16x16x32_bf16 v[30:33], v[130:133], v[184:187], v[30:33]
	v_mfma_f32_16x16x32_bf16 v[26:29], v[138:141], v[184:187], v[26:29]
	v_mfma_f32_16x16x32_bf16 v[14:17], v[130:133], v[192:195], v[14:17]
	v_mfma_f32_16x16x32_bf16 v[10:13], v[138:141], v[192:195], v[10:13]
	v_mfma_f32_16x16x32_bf16 v[62:65], v[134:137], v[172:175], v[62:65]
	v_mfma_f32_16x16x32_bf16 v[58:61], v[142:145], v[172:175], v[58:61]
	v_mfma_f32_16x16x32_bf16 v[46:49], v[134:137], v[180:183], v[46:49]
	v_mfma_f32_16x16x32_bf16 v[42:45], v[142:145], v[180:183], v[42:45]
	v_mfma_f32_16x16x32_bf16 v[30:33], v[134:137], v[188:191], v[30:33]
	v_mfma_f32_16x16x32_bf16 v[26:29], v[142:145], v[188:191], v[26:29]
	v_mfma_f32_16x16x32_bf16 v[14:17], v[134:137], v[200:203], v[14:17]
	v_mfma_f32_16x16x32_bf16 v[10:13], v[142:145], v[200:203], v[10:13]
	v_mfma_f32_16x16x32_bf16 v[54:57], v[146:149], v[168:171], v[54:57]
	v_mfma_f32_16x16x32_bf16 v[50:53], v[154:157], v[168:171], v[50:53]
	v_mfma_f32_16x16x32_bf16 v[38:41], v[146:149], v[176:179], v[38:41]
	v_mfma_f32_16x16x32_bf16 v[34:37], v[154:157], v[176:179], v[34:37]
	v_mfma_f32_16x16x32_bf16 v[22:25], v[146:149], v[184:187], v[22:25]
	v_mfma_f32_16x16x32_bf16 v[18:21], v[154:157], v[184:187], v[18:21]
	v_mfma_f32_16x16x32_bf16 v[6:9], v[146:149], v[192:195], v[6:9]
	v_mfma_f32_16x16x32_bf16 v[2:5], v[154:157], v[192:195], v[2:5]
	v_mfma_f32_16x16x32_bf16 v[54:57], v[150:153], v[172:175], v[54:57]
	v_mfma_f32_16x16x32_bf16 v[50:53], v[164:167], v[172:175], v[50:53]
	v_mfma_f32_16x16x32_bf16 v[38:41], v[150:153], v[180:183], v[38:41]
	v_mfma_f32_16x16x32_bf16 v[34:37], v[164:167], v[180:183], v[34:37]
	v_mfma_f32_16x16x32_bf16 v[22:25], v[150:153], v[188:191], v[22:25]
	v_mfma_f32_16x16x32_bf16 v[18:21], v[164:167], v[188:191], v[18:21]
	v_mfma_f32_16x16x32_bf16 v[6:9], v[150:153], v[200:203], v[6:9]
	v_mfma_f32_16x16x32_bf16 v[2:5], v[164:167], v[200:203], v[2:5]
	s_barrier
	s_setprio 0
	s_add_i32 s59, s59, 2
	s_addk_i32 s2, 0x100
	s_addk_i32 s3, 0x100
	s_cmp_gt_u32 s59, 13
	s_cbranch_scc0 .LBB0_1235
	s_mov_b32 m0, s41
	s_nop 0
	buffer_load_dwordx4 v0, s[20:23], s61 offen lds
	s_mov_b32 m0, s33
	s_nop 0
	buffer_load_dwordx4 v159, s[20:23], s61 offen lds
	v_readlane_b32 s2, v251, 45
	v_readlane_b32 s3, v251, 46
	s_and_b64 vcc, exec, s[2:3]
	s_cbranch_vccz .LBB0_1238
	s_barrier

; #define PG8_WAIT_V(n) asm volatile("s_waitcnt vmcnt(" #n ")" ::: "memory")
; template <class Epi, bool ALIGN_EPI, bool SP2, class Hook>
; __device__ __forceinline__ void gemm_phase(LAS unsigned char* lds, const Gemm g, const StaticOrder& S, const Epi& E, Acc& acc, const bool fresh, const Hook& H, const int wave_id) {
;     ...
;             const bool last = (t == nt - 2);
;             const Src a1 = cA + (size_t)(t + 1) * kstep;
;             const Src a2 = last ? nA : cA + (size_t)(t + 2) * kstep, b2 = last ? nB : cB + (size_t)(t + 2) * kstep;
;             const Src a3 = a2 + kstep, b3 = b2 + kstep;
;             if (last && has_next) H(nxt);
;             if constexpr (SP2) {
;             PG8_TRIP_SP2(PG8_WAIT_V(8));
.LBB0_1461:
	s_add_i32 s100, s55, 0xfffc0000
	v_add_u32_e32 v138, 0x10000, v136
	v_add_u32_e32 v139, 0x14000, v136
	ds_read_b128 v[140:143], v138
	ds_read_b128 v[144:147], v138 offset:1024
	ds_read_b128 v[148:151], v138 offset:2048
	ds_read_b128 v[152:155], v138 offset:3072
	ds_read_b128 v[156:159], v139
	ds_read_b128 v[160:163], v139 offset:1024
	ds_read_b128 v[164:167], v139 offset:2048
	ds_read_b128 v[168:171], v139 offset:3072
	s_mov_b32 m0, s41
	s_nop 0
	buffer_load_dwordx4 v132, s[12:15], s100 offen lds
	s_mov_b32 m0, s33
	s_nop 0
	buffer_load_dwordx4 v134, s[12:15], s100 offen lds
	s_mov_b32 m0, s45
	ds_read_b128 v[172:175], v137
	ds_read_b128 v[176:179], v137 offset:1024
	ds_read_b128 v[180:183], v137 offset:2048
	ds_read_b128 v[184:187], v137 offset:3072
	ds_read_b128 v[188:191], v137 offset:4096
	ds_read_b128 v[192:195], v137 offset:5120
	ds_read_b128 v[200:203], v137 offset:6144
	ds_read_b128 v[204:207], v137 offset:7168
	buffer_load_dwordx4 v132, s[12:15], s55 offen lds
	s_mov_b32 m0, s46
	s_nop 0
	buffer_load_dwordx4 v134, s[12:15], s55 offen lds
	s_waitcnt vmcnt(8)
	s_waitcnt lgkmcnt(0)
	s_setprio 1
	s_barrier
	v_mfma_f32_16x16x32_bf16 v[124:127], v[140:143], v[172:175], v[124:127]
	v_mfma_f32_16x16x32_bf16 v[116:119], v[148:151], v[172:175], v[116:119]
	v_mfma_f32_16x16x32_bf16 v[108:111], v[140:143], v[180:183], v[108:111]
	v_mfma_f32_16x16x32_bf16 v[100:103], v[148:151], v[180:183], v[100:103]
	v_mfma_f32_16x16x32_bf16 v[92:95], v[140:143], v[188:191], v[92:95]
	v_mfma_f32_16x16x32_bf16 v[84:87], v[148:151], v[188:191], v[84:87]
	v_mfma_f32_16x16x32_bf16 v[76:79], v[140:143], v[200:203], v[76:79]
	v_mfma_f32_16x16x32_bf16 v[64:67], v[148:151], v[200:203], v[64:67]
	v_mfma_f32_16x16x32_bf16 v[124:127], v[144:147], v[176:179], v[124:127]
	v_mfma_f32_16x16x32_bf16 v[116:119], v[152:155], v[176:179], v[116:119]
	v_mfma_f32_16x16x32_bf16 v[108:111], v[144:147], v[184:187], v[108:111]
	v_mfma_f32_16x16x32_bf16 v[100:103], v[152:155], v[184:187], v[100:103]
	v_mfma_f32_16x16x32_bf16 v[92:95], v[144:147], v[192:195], v[92:95]
	v_mfma_f32_16x16x32_bf16 v[84:87], v[152:155], v[192:195], v[84:87]
	v_mfma_f32_16x16x32_bf16 v[76:79], v[144:147], v[204:207], v[76:79]
	v_mfma_f32_16x16x32_bf16 v[64:67], v[152:155], v[204:207], v[64:67]
	v_mfma_f32_16x16x32_bf16 v[128:131], v[156:159], v[172:175], v[128:131]
	v_mfma_f32_16x16x32_bf16 v[120:123], v[164:167], v[172:175], v[120:123]
	v_mfma_f32_16x16x32_bf16 v[112:115], v[156:159], v[180:183], v[112:115]
	v_mfma_f32_16x16x32_bf16 v[104:107], v[164:167], v[180:183], v[104:107]
	v_mfma_f32_16x16x32_bf16 v[96:99], v[156:159], v[188:191], v[96:99]
	v_mfma_f32_16x16x32_bf16 v[88:91], v[164:167], v[188:191], v[88:91]
	v_mfma_f32_16x16x32_bf16 v[80:83], v[156:159], v[200:203], v[80:83]
	v_mfma_f32_16x16x32_bf16 v[68:71], v[164:167], v[200:203], v[68:71]
	v_mfma_f32_16x16x32_bf16 v[128:131], v[160:163], v[176:179], v[128:131]
	v_mfma_f32_16x16x32_bf16 v[120:123], v[168:171], v[176:179], v[120:123]
	v_mfma_f32_16x16x32_bf16 v[112:115], v[160:163], v[184:187], v[112:115]
	v_mfma_f32_16x16x32_bf16 v[104:107], v[168:171], v[184:187], v[104:107]
	v_mfma_f32_16x16x32_bf16 v[96:99], v[160:163], v[192:195], v[96:99]
	v_mfma_f32_16x16x32_bf16 v[88:91], v[168:171], v[192:195], v[88:91]
	v_mfma_f32_16x16x32_bf16 v[80:83], v[160:163], v[204:207], v[80:83]
	v_mfma_f32_16x16x32_bf16 v[68:71], v[168:171], v[204:207], v[68:71]
	s_barrier
	s_setprio 0
	s_add_i32 s16, s55, 0xfffc0080
	s_cmp_eq_u32 s54, 12
	s_cselect_b32 s59, s50, s16
	s_cselect_b32 s17, s9, s77
	s_cselect_b32 s16, s8, s76
	s_cselect_b32 s19, s11, s29
	s_cselect_b32 s18, s10, s28
	s_cselect_b32 s57, s51, s56
	s_cselect_b32 s20, s4, s12
	s_cselect_b32 s21, s5, s13
	s_cselect_b32 s22, s6, s14
	s_cselect_b32 s23, s7, s15
	s_or_b32 s58, s59, 0x80
	s_mov_b32 m0, s92
	ds_read_b128 v[172:175], v137 offset:16384
	ds_read_b128 v[176:179], v137 offset:17408
	ds_read_b128 v[180:183], v137 offset:18432
	ds_read_b128 v[184:187], v137 offset:19456
	ds_read_b128 v[188:191], v137 offset:20480
	ds_read_b128 v[192:195], v137 offset:21504
	ds_read_b128 v[200:203], v137 offset:22528
	ds_read_b128 v[204:207], v137 offset:23552
	buffer_load_dwordx4 v133, s[16:19], s57 offen lds
	s_mov_b32 m0, s93
	s_add_i32 s60, s57, 0x40000
	buffer_load_dwordx4 v135, s[16:19], s57 offen lds
	s_mov_b32 m0, s94
	s_nop 0
	buffer_load_dwordx4 v133, s[16:19], s60 offen lds
	s_mov_b32 m0, s95
	s_nop 0
	buffer_load_dwordx4 v135, s[16:19], s60 offen lds
	s_waitcnt vmcnt(6)
	s_waitcnt lgkmcnt(0)
	s_setprio 1
	s_barrier
	v_mfma_f32_16x16x32_bf16 v[60:63], v[140:143], v[172:175], v[60:63]
	v_mfma_f32_16x16x32_bf16 v[52:55], v[148:151], v[172:175], v[52:55]
	v_mfma_f32_16x16x32_bf16 v[44:47], v[140:143], v[180:183], v[44:47]
	v_mfma_f32_16x16x32_bf16 v[36:39], v[148:151], v[180:183], v[36:39]
	v_mfma_f32_16x16x32_bf16 v[28:31], v[140:143], v[188:191], v[28:31]
	v_mfma_f32_16x16x32_bf16 v[20:23], v[148:151], v[188:191], v[20:23]
	v_mfma_f32_16x16x32_bf16 v[12:15], v[140:143], v[200:203], v[12:15]
	v_mfma_f32_16x16x32_bf16 v[2:5], v[148:151], v[200:203], v[4:7]
	v_mfma_f32_16x16x32_bf16 v[60:63], v[144:147], v[176:179], v[60:63]
	v_mfma_f32_16x16x32_bf16 v[52:55], v[152:155], v[176:179], v[52:55]
	v_mfma_f32_16x16x32_bf16 v[44:47], v[144:147], v[184:187], v[44:47]
	v_mfma_f32_16x16x32_bf16 v[36:39], v[152:155], v[184:187], v[36:39]
	v_mfma_f32_16x16x32_bf16 v[28:31], v[144:147], v[192:195], v[28:31]
	v_mfma_f32_16x16x32_bf16 v[20:23], v[152:155], v[192:195], v[20:23]
	v_mfma_f32_16x16x32_bf16 v[12:15], v[144:147], v[204:207], v[12:15]
	v_mfma_f32_16x16x32_bf16 v[2:5], v[152:155], v[204:207], v[2:5]
	v_mfma_f32_16x16x32_bf16 v[72:75], v[156:159], v[172:175], v[72:75]
	v_mfma_f32_16x16x32_bf16 v[56:59], v[164:167], v[172:175], v[56:59]
	v_mfma_f32_16x16x32_bf16 v[48:51], v[156:159], v[180:183], v[48:51]
	v_mfma_f32_16x16x32_bf16 v[40:43], v[164:167], v[180:183], v[40:43]
	v_mfma_f32_16x16x32_bf16 v[32:35], v[156:159], v[188:191], v[32:35]
	v_mfma_f32_16x16x32_bf16 v[24:27], v[164:167], v[188:191], v[24:27]
	v_mfma_f32_16x16x32_bf16 v[16:19], v[156:159], v[200:203], v[16:19]
	v_mfma_f32_16x16x32_bf16 v[6:9], v[164:167], v[200:203], v[8:11]
	v_mfma_f32_16x16x32_bf16 v[72:75], v[160:163], v[176:179], v[72:75]
	v_mfma_f32_16x16x32_bf16 v[56:59], v[168:171], v[176:179], v[56:59]
	v_mfma_f32_16x16x32_bf16 v[48:51], v[160:163], v[184:187], v[48:51]
	v_mfma_f32_16x16x32_bf16 v[40:43], v[168:171], v[184:187], v[40:43]
	v_mfma_f32_16x16x32_bf16 v[32:35], v[160:163], v[192:195], v[32:35]
	v_mfma_f32_16x16x32_bf16 v[24:27], v[168:171], v[192:195], v[24:27]
	v_mfma_f32_16x16x32_bf16 v[16:19], v[160:163], v[204:207], v[16:19]
	v_mfma_f32_16x16x32_bf16 v[8:11], v[168:171], v[204:207], v[6:9]
	s_barrier
	s_setprio 0
	s_mov_b32 m0, s44
	s_nop 0
	buffer_load_dwordx4 v132, s[20:23], s59 offen lds
	s_mov_b32 m0, s36
	s_nop 0
	buffer_load_dwordx4 v134, s[20:23], s59 offen lds
	v_add_u32_e32 v140, 0x18000, v136
	v_add_u32_e32 v141, 0x1c000, v136
	ds_read_b128 v[142:145], v140
	ds_read_b128 v[146:149], v140 offset:1024
	ds_read_b128 v[150:153], v140 offset:2048
	ds_read_b128 v[154:157], v140 offset:3072
	ds_read_b128 v[158:161], v141
	ds_read_b128 v[162:165], v141 offset:1024
	ds_read_b128 v[166:169], v141 offset:2048
	ds_read_b128 v[170:173], v141 offset:3072
	s_add_i32 s59, s59, 0x40000
	s_mov_b32 m0, s37
	ds_read_b128 v[174:177], v137 offset:32768
	ds_read_b128 v[178:181], v137 offset:33792
	ds_read_b128 v[182:185], v137 offset:34816
	ds_read_b128 v[186:189], v137 offset:35840
	ds_read_b128 v[190:193], v137 offset:36864
	ds_read_b128 v[194:197], v137 offset:37888
	ds_read_b128 v[200:203], v137 offset:38912
	ds_read_b128 v[204:207], v137 offset:39936
	buffer_load_dwordx4 v132, s[20:23], s59 offen lds
	s_mov_b32 m0, s38
	s_nop 0
	buffer_load_dwordx4 v134, s[20:23], s59 offen lds
	s_waitcnt vmcnt(8)
	s_waitcnt lgkmcnt(0)
	s_setprio 1
	s_barrier
	v_mfma_f32_16x16x32_bf16 v[124:127], v[142:145], v[174:177], v[124:127]
	v_mfma_f32_16x16x32_bf16 v[116:119], v[150:153], v[174:177], v[116:119]
	v_mfma_f32_16x16x32_bf16 v[108:111], v[142:145], v[182:185], v[108:111]
	v_mfma_f32_16x16x32_bf16 v[100:103], v[150:153], v[182:185], v[100:103]
	v_mfma_f32_16x16x32_bf16 v[92:95], v[142:145], v[190:193], v[92:95]
	v_mfma_f32_16x16x32_bf16 v[84:87], v[150:153], v[190:193], v[84:87]
	v_mfma_f32_16x16x32_bf16 v[76:79], v[142:145], v[200:203], v[76:79]
	v_mfma_f32_16x16x32_bf16 v[64:67], v[150:153], v[200:203], v[64:67]
	v_mfma_f32_16x16x32_bf16 v[124:127], v[146:149], v[178:181], v[124:127]
	v_mfma_f32_16x16x32_bf16 v[116:119], v[154:157], v[178:181], v[116:119]
	v_mfma_f32_16x16x32_bf16 v[108:111], v[146:149], v[186:189], v[108:111]
	v_mfma_f32_16x16x32_bf16 v[100:103], v[154:157], v[186:189], v[100:103]
	v_mfma_f32_16x16x32_bf16 v[92:95], v[146:149], v[194:197], v[92:95]
	v_mfma_f32_16x16x32_bf16 v[84:87], v[154:157], v[194:197], v[84:87]
	v_mfma_f32_16x16x32_bf16 v[76:79], v[146:149], v[204:207], v[76:79]
	v_mfma_f32_16x16x32_bf16 v[64:67], v[154:157], v[204:207], v[64:67]
	v_mfma_f32_16x16x32_bf16 v[128:131], v[158:161], v[174:177], v[128:131]
	v_mfma_f32_16x16x32_bf16 v[120:123], v[166:169], v[174:177], v[120:123]
	v_mfma_f32_16x16x32_bf16 v[112:115], v[158:161], v[182:185], v[112:115]
	v_mfma_f32_16x16x32_bf16 v[104:107], v[166:169], v[182:185], v[104:107]
	v_mfma_f32_16x16x32_bf16 v[96:99], v[158:161], v[190:193], v[96:99]
	v_mfma_f32_16x16x32_bf16 v[88:91], v[166:169], v[190:193], v[88:91]
	v_mfma_f32_16x16x32_bf16 v[80:83], v[158:161], v[200:203], v[80:83]
	v_mfma_f32_16x16x32_bf16 v[68:71], v[166:169], v[200:203], v[68:71]
	v_mfma_f32_16x16x32_bf16 v[128:131], v[162:165], v[178:181], v[128:131]
	v_mfma_f32_16x16x32_bf16 v[120:123], v[170:173], v[178:181], v[120:123]
	v_mfma_f32_16x16x32_bf16 v[112:115], v[162:165], v[186:189], v[112:115]
	v_mfma_f32_16x16x32_bf16 v[104:107], v[170:173], v[186:189], v[104:107]
	v_mfma_f32_16x16x32_bf16 v[96:99], v[162:165], v[194:197], v[96:99]
	v_mfma_f32_16x16x32_bf16 v[88:91], v[170:173], v[194:197], v[88:91]
	v_mfma_f32_16x16x32_bf16 v[80:83], v[162:165], v[204:207], v[80:83]
	v_mfma_f32_16x16x32_bf16 v[68:71], v[170:173], v[204:207], v[68:71]
	s_barrier
; #define PG8_WAIT_V(n) asm volatile("s_waitcnt vmcnt(" #n ")" ::: "memory")
; template <class Epi, bool ALIGN_EPI, bool SP2, class Hook>
; __device__ __forceinline__ void gemm_phase(LAS unsigned char* lds, const Gemm g, const StaticOrder& S, const Epi& E, Acc& acc, const bool fresh, const Hook& H, const int wave_id) {
;     ...
;         for (int t = t0; t < nt; t += 2) {
;             const bool last = (t == nt - 2);
;             const Src a1 = cA + (size_t)(t + 1) * kstep;
;             const Src a2 = last ? nA : cA + (size_t)(t + 2) * kstep, b2 = last ? nB : cB + (size_t)(t + 2) * kstep;
;             const Src a3 = a2 + kstep, b3 = b2 + kstep;
;             if (last && has_next) H(nxt);
;             if constexpr (SP2) {
;             PG8_TRIP_SP2(PG8_WAIT_V(8));
	s_setprio 0
	s_mov_b32 m0, s39
	s_or_b32 s59, s57, 0x80
	ds_read_b128 v[174:177], v137 offset:49152
	ds_read_b128 v[178:181], v137 offset:50176
	ds_read_b128 v[182:185], v137 offset:51200
	ds_read_b128 v[186:189], v137 offset:52224
	ds_read_b128 v[190:193], v137 offset:53248
	ds_read_b128 v[194:197], v137 offset:54272
	ds_read_b128 v[200:203], v137 offset:55296
	ds_read_b128 v[204:207], v137 offset:56320
	buffer_load_dwordx4 v133, s[16:19], s59 offen lds
	s_mov_b32 m0, s40
	s_add_i32 s57, s57, 0x40080
	buffer_load_dwordx4 v135, s[16:19], s59 offen lds
	s_mov_b32 m0, s43
	s_nop 0
	buffer_load_dwordx4 v133, s[16:19], s57 offen lds
	s_mov_b32 m0, s42
	s_nop 0
	buffer_load_dwordx4 v135, s[16:19], s57 offen lds
	s_waitcnt vmcnt(6)
	s_waitcnt lgkmcnt(0)
	s_setprio 1
	s_barrier
	v_mfma_f32_16x16x32_bf16 v[60:63], v[142:145], v[174:177], v[60:63]
	v_mfma_f32_16x16x32_bf16 v[52:55], v[150:153], v[174:177], v[52:55]
	v_mfma_f32_16x16x32_bf16 v[44:47], v[142:145], v[182:185], v[44:47]
	v_mfma_f32_16x16x32_bf16 v[36:39], v[150:153], v[182:185], v[36:39]
	v_mfma_f32_16x16x32_bf16 v[28:31], v[142:145], v[190:193], v[28:31]
	v_mfma_f32_16x16x32_bf16 v[20:23], v[150:153], v[190:193], v[20:23]
	v_mfma_f32_16x16x32_bf16 v[12:15], v[142:145], v[200:203], v[12:15]
	v_mfma_f32_16x16x32_bf16 v[2:5], v[150:153], v[200:203], v[2:5]
	v_mfma_f32_16x16x32_bf16 v[60:63], v[146:149], v[178:181], v[60:63]
	v_mfma_f32_16x16x32_bf16 v[52:55], v[154:157], v[178:181], v[52:55]
	v_mfma_f32_16x16x32_bf16 v[44:47], v[146:149], v[186:189], v[44:47]
	v_mfma_f32_16x16x32_bf16 v[36:39], v[154:157], v[186:189], v[36:39]
	v_mfma_f32_16x16x32_bf16 v[28:31], v[146:149], v[194:197], v[28:31]
	v_mfma_f32_16x16x32_bf16 v[20:23], v[154:157], v[194:197], v[20:23]
	v_mfma_f32_16x16x32_bf16 v[12:15], v[146:149], v[204:207], v[12:15]
	v_mfma_f32_16x16x32_bf16 v[4:7], v[154:157], v[204:207], v[2:5]
	v_mfma_f32_16x16x32_bf16 v[72:75], v[158:161], v[174:177], v[72:75]
	v_mfma_f32_16x16x32_bf16 v[56:59], v[166:169], v[174:177], v[56:59]
	v_mfma_f32_16x16x32_bf16 v[48:51], v[158:161], v[182:185], v[48:51]
	v_mfma_f32_16x16x32_bf16 v[40:43], v[166:169], v[182:185], v[40:43]
	v_mfma_f32_16x16x32_bf16 v[32:35], v[158:161], v[190:193], v[32:35]
	v_mfma_f32_16x16x32_bf16 v[24:27], v[166:169], v[190:193], v[24:27]
	v_mfma_f32_16x16x32_bf16 v[16:19], v[158:161], v[200:203], v[16:19]
	v_mfma_f32_16x16x32_bf16 v[8:11], v[166:169], v[200:203], v[8:11]
	v_mfma_f32_16x16x32_bf16 v[72:75], v[162:165], v[178:181], v[72:75]
	v_mfma_f32_16x16x32_bf16 v[56:59], v[170:173], v[178:181], v[56:59]
	v_mfma_f32_16x16x32_bf16 v[48:51], v[162:165], v[186:189], v[48:51]
	v_mfma_f32_16x16x32_bf16 v[40:43], v[170:173], v[186:189], v[40:43]
	v_mfma_f32_16x16x32_bf16 v[32:35], v[162:165], v[194:197], v[32:35]
	v_mfma_f32_16x16x32_bf16 v[24:27], v[170:173], v[194:197], v[24:27]
	v_mfma_f32_16x16x32_bf16 v[16:19], v[162:165], v[204:207], v[16:19]
	v_mfma_f32_16x16x32_bf16 v[8:11], v[170:173], v[204:207], v[8:11]
	s_barrier
	s_setprio 0
	s_add_i32 s54, s54, 2
	s_addk_i32 s55, 0x100
	s_addk_i32 s56, 0x100
	s_cmp_gt_u32 s54, 13
	s_cbranch_scc0 .LBB0_1461
	s_mov_b32 m0, s41
	s_nop 0
	buffer_load_dwordx4 v132, s[20:23], s58 offen lds
	s_mov_b32 m0, s33
	s_nop 0
	buffer_load_dwordx4 v134, s[20:23], s58 offen lds
	v_readlane_b32 s12, v251, 45
	v_readlane_b32 s13, v251, 46
	s_and_b64 vcc, exec, s[12:13]
	s_cbranch_vccz .LBB0_1464
	s_barrier

; #define PG8_WAIT_V(n) asm volatile("s_waitcnt vmcnt(" #n ")" ::: "memory")
; template <class Epi, bool ALIGN_EPI, bool SP2, class Hook>
; __device__ __forceinline__ void gemm_phase(LAS unsigned char* lds, const Gemm g, const StaticOrder& S, const Epi& E, Acc& acc, const bool fresh, const Hook& H, const int wave_id) {
;     ...
;             const bool last = (t == nt - 2);
;             const Src a1 = cA + (size_t)(t + 1) * kstep;
;             const Src a2 = last ? nA : cA + (size_t)(t + 2) * kstep, b2 = last ? nB : cB + (size_t)(t + 2) * kstep;
;             const Src a3 = a2 + kstep, b3 = b2 + kstep;
;             if (last && has_next) H(nxt);
;             if constexpr (SP2) {
;             PG8_TRIP_SP2(PG8_WAIT_V(8));
.LBB0_1572:
	s_add_i32 s100, s2, 0xfff40000
	v_add_u32_e32 v142, 0x10000, v161
	v_add_u32_e32 v163, 0x14000, v161
	ds_read_b128 v[130:133], v142
	ds_read_b128 v[134:137], v142 offset:1024
	ds_read_b128 v[138:141], v142 offset:2048
	ds_read_b128 v[142:145], v142 offset:3072
	ds_read_b128 v[146:149], v163
	ds_read_b128 v[150:153], v163 offset:1024
	ds_read_b128 v[154:157], v163 offset:2048
	ds_read_b128 v[164:167], v163 offset:3072
	s_mov_b32 m0, s41
	s_nop 0
	buffer_load_dwordx4 v0, s[12:15], s100 offen lds
	s_mov_b32 m0, s33
	s_nop 0
	buffer_load_dwordx4 v159, s[12:15], s100 offen lds
	s_mov_b32 m0, s45
	ds_read_b128 v[168:171], v162
	ds_read_b128 v[172:175], v162 offset:1024
	ds_read_b128 v[176:179], v162 offset:2048
	ds_read_b128 v[180:183], v162 offset:3072
	ds_read_b128 v[184:187], v162 offset:4096
	ds_read_b128 v[188:191], v162 offset:5120
	ds_read_b128 v[192:195], v162 offset:6144
	ds_read_b128 v[200:203], v162 offset:7168
	buffer_load_dwordx4 v0, s[12:15], s2 offen lds
	s_mov_b32 m0, s46
	s_nop 0
	buffer_load_dwordx4 v159, s[12:15], s2 offen lds
	s_waitcnt vmcnt(8)
	s_waitcnt lgkmcnt(0)
	s_setprio 1
	s_barrier
	v_mfma_f32_16x16x32_bf16 v[126:129], v[130:133], v[168:171], v[126:129]
	v_mfma_f32_16x16x32_bf16 v[122:125], v[138:141], v[168:171], v[122:125]
	v_mfma_f32_16x16x32_bf16 v[110:113], v[130:133], v[176:179], v[110:113]
	v_mfma_f32_16x16x32_bf16 v[106:109], v[138:141], v[176:179], v[106:109]
	v_mfma_f32_16x16x32_bf16 v[94:97], v[130:133], v[184:187], v[94:97]
	v_mfma_f32_16x16x32_bf16 v[90:93], v[138:141], v[184:187], v[90:93]
	v_mfma_f32_16x16x32_bf16 v[78:81], v[130:133], v[192:195], v[78:81]
	v_mfma_f32_16x16x32_bf16 v[74:77], v[138:141], v[192:195], v[74:77]
	v_mfma_f32_16x16x32_bf16 v[126:129], v[134:137], v[172:175], v[126:129]
	v_mfma_f32_16x16x32_bf16 v[122:125], v[142:145], v[172:175], v[122:125]
	v_mfma_f32_16x16x32_bf16 v[110:113], v[134:137], v[180:183], v[110:113]
	v_mfma_f32_16x16x32_bf16 v[106:109], v[142:145], v[180:183], v[106:109]
	v_mfma_f32_16x16x32_bf16 v[94:97], v[134:137], v[188:191], v[94:97]
	v_mfma_f32_16x16x32_bf16 v[90:93], v[142:145], v[188:191], v[90:93]
	v_mfma_f32_16x16x32_bf16 v[78:81], v[134:137], v[200:203], v[78:81]
	v_mfma_f32_16x16x32_bf16 v[74:77], v[142:145], v[200:203], v[74:77]
	v_mfma_f32_16x16x32_bf16 v[118:121], v[146:149], v[168:171], v[118:121]
	v_mfma_f32_16x16x32_bf16 v[114:117], v[154:157], v[168:171], v[114:117]
	v_mfma_f32_16x16x32_bf16 v[102:105], v[146:149], v[176:179], v[102:105]
	v_mfma_f32_16x16x32_bf16 v[98:101], v[154:157], v[176:179], v[98:101]
	v_mfma_f32_16x16x32_bf16 v[86:89], v[146:149], v[184:187], v[86:89]
	v_mfma_f32_16x16x32_bf16 v[82:85], v[154:157], v[184:187], v[82:85]
	v_mfma_f32_16x16x32_bf16 v[70:73], v[146:149], v[192:195], v[70:73]
	v_mfma_f32_16x16x32_bf16 v[66:69], v[154:157], v[192:195], v[66:69]
	v_mfma_f32_16x16x32_bf16 v[118:121], v[150:153], v[172:175], v[118:121]
	v_mfma_f32_16x16x32_bf16 v[114:117], v[164:167], v[172:175], v[114:117]
	v_mfma_f32_16x16x32_bf16 v[102:105], v[150:153], v[180:183], v[102:105]
	v_mfma_f32_16x16x32_bf16 v[98:101], v[164:167], v[180:183], v[98:101]
	v_mfma_f32_16x16x32_bf16 v[86:89], v[150:153], v[188:191], v[86:89]
	v_mfma_f32_16x16x32_bf16 v[82:85], v[164:167], v[188:191], v[82:85]
	v_mfma_f32_16x16x32_bf16 v[70:73], v[150:153], v[200:203], v[70:73]
	v_mfma_f32_16x16x32_bf16 v[66:69], v[164:167], v[200:203], v[66:69]
	s_barrier
	s_setprio 0
	s_add_i32 s16, s2, 0xfff40080
	s_cmp_eq_u32 s61, 40
	s_cselect_b32 s64, s57, s16
	s_cselect_b32 s17, s35, s9
	s_cselect_b32 s16, s34, s8
	s_cselect_b32 s19, s51, s53
	s_cselect_b32 s18, s50, s52
	s_cselect_b32 s62, s58, s3
	s_cselect_b32 s20, s10, s12
	s_cselect_b32 s21, s11, s13
	s_cselect_b32 s22, s30, s14
	s_cselect_b32 s23, s31, s15
	s_or_b32 s63, s64, 0x80
	s_mov_b32 m0, s92
	ds_read_b128 v[168:171], v162 offset:16384
	ds_read_b128 v[172:175], v162 offset:17408
	ds_read_b128 v[176:179], v162 offset:18432
	ds_read_b128 v[180:183], v162 offset:19456
	ds_read_b128 v[184:187], v162 offset:20480
	ds_read_b128 v[188:191], v162 offset:21504
	ds_read_b128 v[192:195], v162 offset:22528
	ds_read_b128 v[200:203], v162 offset:23552
	buffer_load_dwordx4 v158, s[16:19], s62 offen lds
	s_mov_b32 m0, s93
	s_add_i32 s65, s62, 0xb0000
	buffer_load_dwordx4 v160, s[16:19], s62 offen lds
	s_mov_b32 m0, s94
	s_nop 0
	buffer_load_dwordx4 v158, s[16:19], s65 offen lds
	s_mov_b32 m0, s95
	s_nop 0
	buffer_load_dwordx4 v160, s[16:19], s65 offen lds
	s_waitcnt vmcnt(6)
	s_waitcnt lgkmcnt(0)
	s_setprio 1
	s_barrier
	v_mfma_f32_16x16x32_bf16 v[62:65], v[130:133], v[168:171], v[62:65]
	v_mfma_f32_16x16x32_bf16 v[58:61], v[138:141], v[168:171], v[58:61]
	v_mfma_f32_16x16x32_bf16 v[46:49], v[130:133], v[176:179], v[46:49]
	v_mfma_f32_16x16x32_bf16 v[42:45], v[138:141], v[176:179], v[42:45]
	v_mfma_f32_16x16x32_bf16 v[30:33], v[130:133], v[184:187], v[30:33]
	v_mfma_f32_16x16x32_bf16 v[26:29], v[138:141], v[184:187], v[26:29]
	v_mfma_f32_16x16x32_bf16 v[14:17], v[130:133], v[192:195], v[14:17]
	v_mfma_f32_16x16x32_bf16 v[10:13], v[138:141], v[192:195], v[10:13]
	v_mfma_f32_16x16x32_bf16 v[62:65], v[134:137], v[172:175], v[62:65]
	v_mfma_f32_16x16x32_bf16 v[58:61], v[142:145], v[172:175], v[58:61]
	v_mfma_f32_16x16x32_bf16 v[46:49], v[134:137], v[180:183], v[46:49]
	v_mfma_f32_16x16x32_bf16 v[42:45], v[142:145], v[180:183], v[42:45]
	v_mfma_f32_16x16x32_bf16 v[30:33], v[134:137], v[188:191], v[30:33]
	v_mfma_f32_16x16x32_bf16 v[26:29], v[142:145], v[188:191], v[26:29]
	v_mfma_f32_16x16x32_bf16 v[14:17], v[134:137], v[200:203], v[14:17]
	v_mfma_f32_16x16x32_bf16 v[10:13], v[142:145], v[200:203], v[10:13]
	v_mfma_f32_16x16x32_bf16 v[54:57], v[146:149], v[168:171], v[54:57]
	v_mfma_f32_16x16x32_bf16 v[50:53], v[154:157], v[168:171], v[50:53]
	v_mfma_f32_16x16x32_bf16 v[38:41], v[146:149], v[176:179], v[38:41]
	v_mfma_f32_16x16x32_bf16 v[34:37], v[154:157], v[176:179], v[34:37]
	v_mfma_f32_16x16x32_bf16 v[22:25], v[146:149], v[184:187], v[22:25]
	v_mfma_f32_16x16x32_bf16 v[18:21], v[154:157], v[184:187], v[18:21]
	v_mfma_f32_16x16x32_bf16 v[6:9], v[146:149], v[192:195], v[6:9]
	v_mfma_f32_16x16x32_bf16 v[2:5], v[154:157], v[192:195], v[2:5]
	v_mfma_f32_16x16x32_bf16 v[54:57], v[150:153], v[172:175], v[54:57]
	v_mfma_f32_16x16x32_bf16 v[50:53], v[164:167], v[172:175], v[50:53]
	v_mfma_f32_16x16x32_bf16 v[38:41], v[150:153], v[180:183], v[38:41]
	v_mfma_f32_16x16x32_bf16 v[34:37], v[164:167], v[180:183], v[34:37]
	v_mfma_f32_16x16x32_bf16 v[22:25], v[150:153], v[188:191], v[22:25]
	v_mfma_f32_16x16x32_bf16 v[18:21], v[164:167], v[188:191], v[18:21]
	v_mfma_f32_16x16x32_bf16 v[6:9], v[150:153], v[200:203], v[6:9]
	v_mfma_f32_16x16x32_bf16 v[2:5], v[164:167], v[200:203], v[2:5]
	s_barrier
; #define PG8_WAIT_V(n) asm volatile("s_waitcnt vmcnt(" #n ")" ::: "memory")
; template <class Epi, bool ALIGN_EPI, bool SP2, class Hook>
; __device__ __forceinline__ void gemm_phase(LAS unsigned char* lds, const Gemm g, const StaticOrder& S, const Epi& E, Acc& acc, const bool fresh, const Hook& H, const int wave_id) {
;     ...
;         for (int t = t0; t < nt; t += 2) {
;             const bool last = (t == nt - 2);
;             const Src a1 = cA + (size_t)(t + 1) * kstep;
;             const Src a2 = last ? nA : cA + (size_t)(t + 2) * kstep, b2 = last ? nB : cB + (size_t)(t + 2) * kstep;
;             const Src a3 = a2 + kstep, b3 = b2 + kstep;
;             if (last && has_next) H(nxt);
;             if constexpr (SP2) {
;             PG8_TRIP_SP2(PG8_WAIT_V(8));
	s_setprio 0
	s_mov_b32 m0, s44
	s_nop 0
	buffer_load_dwordx4 v0, s[20:23], s64 offen lds
	s_mov_b32 m0, s36
	s_nop 0
	buffer_load_dwordx4 v159, s[20:23], s64 offen lds
	v_add_u32_e32 v142, 0x18000, v161
	v_add_u32_e32 v163, 0x1c000, v161
	ds_read_b128 v[130:133], v142
	ds_read_b128 v[134:137], v142 offset:1024
	ds_read_b128 v[138:141], v142 offset:2048
	ds_read_b128 v[142:145], v142 offset:3072
	ds_read_b128 v[146:149], v163
	ds_read_b128 v[150:153], v163 offset:1024
	ds_read_b128 v[154:157], v163 offset:2048
	ds_read_b128 v[164:167], v163 offset:3072
	s_add_i32 s64, s64, 0xc0000
	s_mov_b32 m0, s37
	ds_read_b128 v[168:171], v162 offset:32768
	ds_read_b128 v[172:175], v162 offset:33792
	ds_read_b128 v[176:179], v162 offset:34816
	ds_read_b128 v[180:183], v162 offset:35840
	ds_read_b128 v[184:187], v162 offset:36864
	ds_read_b128 v[188:191], v162 offset:37888
	ds_read_b128 v[192:195], v162 offset:38912
	ds_read_b128 v[200:203], v162 offset:39936
	buffer_load_dwordx4 v0, s[20:23], s64 offen lds
	s_mov_b32 m0, s38
	s_nop 0
	buffer_load_dwordx4 v159, s[20:23], s64 offen lds
	s_waitcnt vmcnt(8)
	s_waitcnt lgkmcnt(0)
	s_setprio 1
	s_barrier
	v_mfma_f32_16x16x32_bf16 v[126:129], v[130:133], v[168:171], v[126:129]
	v_mfma_f32_16x16x32_bf16 v[122:125], v[138:141], v[168:171], v[122:125]
	v_mfma_f32_16x16x32_bf16 v[110:113], v[130:133], v[176:179], v[110:113]
	v_mfma_f32_16x16x32_bf16 v[106:109], v[138:141], v[176:179], v[106:109]
	v_mfma_f32_16x16x32_bf16 v[94:97], v[130:133], v[184:187], v[94:97]
	v_mfma_f32_16x16x32_bf16 v[90:93], v[138:141], v[184:187], v[90:93]
	v_mfma_f32_16x16x32_bf16 v[78:81], v[130:133], v[192:195], v[78:81]
	v_mfma_f32_16x16x32_bf16 v[74:77], v[138:141], v[192:195], v[74:77]
	v_mfma_f32_16x16x32_bf16 v[126:129], v[134:137], v[172:175], v[126:129]
	v_mfma_f32_16x16x32_bf16 v[122:125], v[142:145], v[172:175], v[122:125]
	v_mfma_f32_16x16x32_bf16 v[110:113], v[134:137], v[180:183], v[110:113]
	v_mfma_f32_16x16x32_bf16 v[106:109], v[142:145], v[180:183], v[106:109]
	v_mfma_f32_16x16x32_bf16 v[94:97], v[134:137], v[188:191], v[94:97]
	v_mfma_f32_16x16x32_bf16 v[90:93], v[142:145], v[188:191], v[90:93]
	v_mfma_f32_16x16x32_bf16 v[78:81], v[134:137], v[200:203], v[78:81]
	v_mfma_f32_16x16x32_bf16 v[74:77], v[142:145], v[200:203], v[74:77]
	v_mfma_f32_16x16x32_bf16 v[118:121], v[146:149], v[168:171], v[118:121]
	v_mfma_f32_16x16x32_bf16 v[114:117], v[154:157], v[168:171], v[114:117]
	v_mfma_f32_16x16x32_bf16 v[102:105], v[146:149], v[176:179], v[102:105]
	v_mfma_f32_16x16x32_bf16 v[98:101], v[154:157], v[176:179], v[98:101]
	v_mfma_f32_16x16x32_bf16 v[86:89], v[146:149], v[184:187], v[86:89]
	v_mfma_f32_16x16x32_bf16 v[82:85], v[154:157], v[184:187], v[82:85]
	v_mfma_f32_16x16x32_bf16 v[70:73], v[146:149], v[192:195], v[70:73]
	v_mfma_f32_16x16x32_bf16 v[66:69], v[154:157], v[192:195], v[66:69]
	v_mfma_f32_16x16x32_bf16 v[118:121], v[150:153], v[172:175], v[118:121]
	v_mfma_f32_16x16x32_bf16 v[114:117], v[164:167], v[172:175], v[114:117]
	v_mfma_f32_16x16x32_bf16 v[102:105], v[150:153], v[180:183], v[102:105]
	v_mfma_f32_16x16x32_bf16 v[98:101], v[164:167], v[180:183], v[98:101]
	v_mfma_f32_16x16x32_bf16 v[86:89], v[150:153], v[188:191], v[86:89]
	v_mfma_f32_16x16x32_bf16 v[82:85], v[164:167], v[188:191], v[82:85]
	v_mfma_f32_16x16x32_bf16 v[70:73], v[150:153], v[200:203], v[70:73]
	v_mfma_f32_16x16x32_bf16 v[66:69], v[164:167], v[200:203], v[66:69]
	s_barrier
	s_setprio 0
	s_mov_b32 m0, s39
	s_or_b32 s64, s62, 0x80
	ds_read_b128 v[168:171], v162 offset:49152
	ds_read_b128 v[172:175], v162 offset:50176
	ds_read_b128 v[176:179], v162 offset:51200
	ds_read_b128 v[180:183], v162 offset:52224
	ds_read_b128 v[184:187], v162 offset:53248
	ds_read_b128 v[188:191], v162 offset:54272
	ds_read_b128 v[192:195], v162 offset:55296
	ds_read_b128 v[200:203], v162 offset:56320
	buffer_load_dwordx4 v158, s[16:19], s64 offen lds
	s_mov_b32 m0, s40
	s_add_i32 s62, s62, 0xb0080
	buffer_load_dwordx4 v160, s[16:19], s64 offen lds
	s_mov_b32 m0, s43
	s_nop 0
	buffer_load_dwordx4 v158, s[16:19], s62 offen lds
	s_mov_b32 m0, s42
	s_nop 0
	buffer_load_dwordx4 v160, s[16:19], s62 offen lds
	s_waitcnt vmcnt(6)
	s_waitcnt lgkmcnt(0)
	s_setprio 1
	s_barrier
	v_mfma_f32_16x16x32_bf16 v[62:65], v[130:133], v[168:171], v[62:65]
	v_mfma_f32_16x16x32_bf16 v[58:61], v[138:141], v[168:171], v[58:61]
	v_mfma_f32_16x16x32_bf16 v[46:49], v[130:133], v[176:179], v[46:49]
	v_mfma_f32_16x16x32_bf16 v[42:45], v[138:141], v[176:179], v[42:45]
	v_mfma_f32_16x16x32_bf16 v[30:33], v[130:133], v[184:187], v[30:33]
	v_mfma_f32_16x16x32_bf16 v[26:29], v[138:141], v[184:187], v[26:29]
	v_mfma_f32_16x16x32_bf16 v[14:17], v[130:133], v[192:195], v[14:17]
	v_mfma_f32_16x16x32_bf16 v[10:13], v[138:141], v[192:195], v[10:13]
	v_mfma_f32_16x16x32_bf16 v[62:65], v[134:137], v[172:175], v[62:65]
	v_mfma_f32_16x16x32_bf16 v[58:61], v[142:145], v[172:175], v[58:61]
	v_mfma_f32_16x16x32_bf16 v[46:49], v[134:137], v[180:183], v[46:49]
	v_mfma_f32_16x16x32_bf16 v[42:45], v[142:145], v[180:183], v[42:45]
	v_mfma_f32_16x16x32_bf16 v[30:33], v[134:137], v[188:191], v[30:33]
	v_mfma_f32_16x16x32_bf16 v[26:29], v[142:145], v[188:191], v[26:29]
	v_mfma_f32_16x16x32_bf16 v[14:17], v[134:137], v[200:203], v[14:17]
	v_mfma_f32_16x16x32_bf16 v[10:13], v[142:145], v[200:203], v[10:13]
	v_mfma_f32_16x16x32_bf16 v[54:57], v[146:149], v[168:171], v[54:57]
	v_mfma_f32_16x16x32_bf16 v[50:53], v[154:157], v[168:171], v[50:53]
	v_mfma_f32_16x16x32_bf16 v[38:41], v[146:149], v[176:179], v[38:41]
	v_mfma_f32_16x16x32_bf16 v[34:37], v[154:157], v[176:179], v[34:37]
	v_mfma_f32_16x16x32_bf16 v[22:25], v[146:149], v[184:187], v[22:25]
	v_mfma_f32_16x16x32_bf16 v[18:21], v[154:157], v[184:187], v[18:21]
	v_mfma_f32_16x16x32_bf16 v[6:9], v[146:149], v[192:195], v[6:9]
	v_mfma_f32_16x16x32_bf16 v[2:5], v[154:157], v[192:195], v[2:5]
	v_mfma_f32_16x16x32_bf16 v[54:57], v[150:153], v[172:175], v[54:57]
	v_mfma_f32_16x16x32_bf16 v[50:53], v[164:167], v[172:175], v[50:53]
	v_mfma_f32_16x16x32_bf16 v[38:41], v[150:153], v[180:183], v[38:41]
	v_mfma_f32_16x16x32_bf16 v[34:37], v[164:167], v[180:183], v[34:37]
	v_mfma_f32_16x16x32_bf16 v[22:25], v[150:153], v[188:191], v[22:25]
	v_mfma_f32_16x16x32_bf16 v[18:21], v[164:167], v[188:191], v[18:21]
	v_mfma_f32_16x16x32_bf16 v[6:9], v[150:153], v[200:203], v[6:9]
	v_mfma_f32_16x16x32_bf16 v[2:5], v[164:167], v[200:203], v[2:5]
	s_barrier
	s_setprio 0
	s_add_i32 s61, s61, 2
	s_addk_i32 s2, 0x100
	s_addk_i32 s3, 0x100
	s_cmp_gt_u32 s61, 41
	s_cbranch_scc0 .LBB0_1572
	s_mov_b32 m0, s41
	s_nop 0
	buffer_load_dwordx4 v0, s[20:23], s63 offen lds
	s_mov_b32 m0, s33
	s_nop 0
	buffer_load_dwordx4 v159, s[20:23], s63 offen lds
	v_readlane_b32 s2, v251, 45
	v_readlane_b32 s3, v251, 46
	s_and_b64 vcc, exec, s[2:3]
	s_cbranch_vccz .LBB0_1575
	s_barrier

; #define PG8_WAIT_V(n) asm volatile("s_waitcnt vmcnt(" #n ")" ::: "memory")
; template <class Epi, bool ALIGN_EPI, bool SP2, class Hook>
; __device__ __forceinline__ void gemm_phase(LAS unsigned char* lds, const Gemm g, const StaticOrder& S, const Epi& E, Acc& acc, const bool fresh, const Hook& H, const int wave_id) {
;     ...
;             const bool last = (t == nt - 2);
;             const Src a1 = cA + (size_t)(t + 1) * kstep;
;             const Src a2 = last ? nA : cA + (size_t)(t + 2) * kstep, b2 = last ? nB : cB + (size_t)(t + 2) * kstep;
;             const Src a3 = a2 + kstep, b3 = b2 + kstep;
;             if (last && has_next) H(nxt);
;             if constexpr (SP2) {
;             PG8_TRIP_SP2(PG8_WAIT_V(8));
.LBB0_1614:
	s_add_i32 s100, s2, 0xfff40000
	v_add_u32_e32 v0, 0x10000, v172
	ds_read_b128 v[130:133], v0
	ds_read_b128 v[134:137], v0 offset:1024
	ds_read_b128 v[138:141], v0 offset:2048
	ds_read_b128 v[142:145], v0 offset:3072
	v_add_u32_e32 v0, 0x14000, v172
	ds_read_b128 v[146:149], v0
	ds_read_b128 v[150:153], v0 offset:1024
	ds_read_b128 v[154:157], v0 offset:2048
	ds_read_b128 v[158:161], v0 offset:3072
	s_mov_b32 m0, s41
	s_nop 0
	buffer_load_dwordx4 v168, s[8:11], s100 offen lds
	s_mov_b32 m0, s33
	s_nop 0
	buffer_load_dwordx4 v170, s[8:11], s100 offen lds
	s_mov_b32 m0, s45
	ds_read_b128 v[162:165], v173
	ds_read_b128 v[174:177], v173 offset:1024
	ds_read_b128 v[178:181], v173 offset:2048
	ds_read_b128 v[182:185], v173 offset:3072
	ds_read_b128 v[186:189], v173 offset:4096
	ds_read_b128 v[190:193], v173 offset:5120
	ds_read_b128 v[194:197], v173 offset:6144
	ds_read_b128 v[200:203], v173 offset:7168
	buffer_load_dwordx4 v168, s[8:11], s2 offen lds
	s_mov_b32 m0, s46
	s_nop 0
	buffer_load_dwordx4 v170, s[8:11], s2 offen lds
	s_waitcnt vmcnt(8)
	s_waitcnt lgkmcnt(0)
	s_setprio 1
	s_barrier
	v_mfma_f32_16x16x32_bf16 v[126:129], v[130:133], v[162:165], v[126:129]
	v_mfma_f32_16x16x32_bf16 v[122:125], v[138:141], v[162:165], v[122:125]
	v_mfma_f32_16x16x32_bf16 v[110:113], v[130:133], v[178:181], v[110:113]
	v_mfma_f32_16x16x32_bf16 v[106:109], v[138:141], v[178:181], v[106:109]
	v_mfma_f32_16x16x32_bf16 v[94:97], v[130:133], v[186:189], v[94:97]
	v_mfma_f32_16x16x32_bf16 v[90:93], v[138:141], v[186:189], v[90:93]
	v_mfma_f32_16x16x32_bf16 v[78:81], v[130:133], v[194:197], v[78:81]
	v_mfma_f32_16x16x32_bf16 v[74:77], v[138:141], v[194:197], v[74:77]
	v_mfma_f32_16x16x32_bf16 v[126:129], v[134:137], v[174:177], v[126:129]
	v_mfma_f32_16x16x32_bf16 v[122:125], v[142:145], v[174:177], v[122:125]
	v_mfma_f32_16x16x32_bf16 v[110:113], v[134:137], v[182:185], v[110:113]
	v_mfma_f32_16x16x32_bf16 v[106:109], v[142:145], v[182:185], v[106:109]
	v_mfma_f32_16x16x32_bf16 v[94:97], v[134:137], v[190:193], v[94:97]
	v_mfma_f32_16x16x32_bf16 v[90:93], v[142:145], v[190:193], v[90:93]
	v_mfma_f32_16x16x32_bf16 v[78:81], v[134:137], v[200:203], v[78:81]
	v_mfma_f32_16x16x32_bf16 v[74:77], v[142:145], v[200:203], v[74:77]
	v_mfma_f32_16x16x32_bf16 v[118:121], v[146:149], v[162:165], v[118:121]
	v_mfma_f32_16x16x32_bf16 v[114:117], v[154:157], v[162:165], v[114:117]
	v_mfma_f32_16x16x32_bf16 v[102:105], v[146:149], v[178:181], v[102:105]
	v_mfma_f32_16x16x32_bf16 v[98:101], v[154:157], v[178:181], v[98:101]
	v_mfma_f32_16x16x32_bf16 v[86:89], v[146:149], v[186:189], v[86:89]
	v_mfma_f32_16x16x32_bf16 v[82:85], v[154:157], v[186:189], v[82:85]
	v_mfma_f32_16x16x32_bf16 v[70:73], v[146:149], v[194:197], v[70:73]
	v_mfma_f32_16x16x32_bf16 v[66:69], v[154:157], v[194:197], v[66:69]
	v_mfma_f32_16x16x32_bf16 v[118:121], v[150:153], v[174:177], v[118:121]
	v_mfma_f32_16x16x32_bf16 v[114:117], v[158:161], v[174:177], v[114:117]
	v_mfma_f32_16x16x32_bf16 v[102:105], v[150:153], v[182:185], v[102:105]
	v_mfma_f32_16x16x32_bf16 v[98:101], v[158:161], v[182:185], v[98:101]
	v_mfma_f32_16x16x32_bf16 v[86:89], v[150:153], v[190:193], v[86:89]
	v_mfma_f32_16x16x32_bf16 v[82:85], v[158:161], v[190:193], v[82:85]
	v_mfma_f32_16x16x32_bf16 v[70:73], v[150:153], v[200:203], v[70:73]
	v_mfma_f32_16x16x32_bf16 v[66:69], v[158:161], v[200:203], v[66:69]
	s_barrier
	s_setprio 0
	s_add_i32 s12, s2, 0xfff40080
	s_cmp_eq_u32 s59, 40
	s_cselect_b32 s62, s55, s12
	s_cselect_b32 s13, s31, s77
	s_cselect_b32 s12, s30, s76
	s_cselect_b32 s15, s35, s51
	s_cselect_b32 s14, s34, s50
	s_cselect_b32 s60, s56, s3
	s_cselect_b32 s16, s20, s8
	s_cselect_b32 s17, s21, s9
	s_cselect_b32 s18, s22, s10
	s_cselect_b32 s19, s23, s11
	s_or_b32 s61, s62, 0x80
	s_mov_b32 m0, s92
	ds_read_b128 v[162:165], v173 offset:16384
	ds_read_b128 v[174:177], v173 offset:17408
	ds_read_b128 v[178:181], v173 offset:18432
	ds_read_b128 v[182:185], v173 offset:19456
	ds_read_b128 v[186:189], v173 offset:20480
	ds_read_b128 v[190:193], v173 offset:21504
	ds_read_b128 v[194:197], v173 offset:22528
	ds_read_b128 v[200:203], v173 offset:23552
	buffer_load_dwordx4 v169, s[12:15], s60 offen lds
	s_mov_b32 m0, s93
	s_add_i32 s63, s60, 0xb0000
	buffer_load_dwordx4 v171, s[12:15], s60 offen lds
	s_mov_b32 m0, s94
	s_nop 0
	buffer_load_dwordx4 v169, s[12:15], s63 offen lds
	s_mov_b32 m0, s95
	s_nop 0
	buffer_load_dwordx4 v171, s[12:15], s63 offen lds
	s_waitcnt vmcnt(6)
	s_waitcnt lgkmcnt(0)
	s_setprio 1
	s_barrier
	v_mfma_f32_16x16x32_bf16 v[62:65], v[130:133], v[162:165], v[62:65]
	v_mfma_f32_16x16x32_bf16 v[58:61], v[138:141], v[162:165], v[58:61]
	v_mfma_f32_16x16x32_bf16 v[46:49], v[130:133], v[178:181], v[46:49]
	v_mfma_f32_16x16x32_bf16 v[42:45], v[138:141], v[178:181], v[42:45]
	v_mfma_f32_16x16x32_bf16 v[30:33], v[130:133], v[186:189], v[30:33]
	v_mfma_f32_16x16x32_bf16 v[26:29], v[138:141], v[186:189], v[26:29]
	v_mfma_f32_16x16x32_bf16 v[14:17], v[130:133], v[194:197], v[14:17]
	v_mfma_f32_16x16x32_bf16 v[10:13], v[138:141], v[194:197], v[10:13]
	v_mfma_f32_16x16x32_bf16 v[62:65], v[134:137], v[174:177], v[62:65]
	v_mfma_f32_16x16x32_bf16 v[58:61], v[142:145], v[174:177], v[58:61]
	v_mfma_f32_16x16x32_bf16 v[46:49], v[134:137], v[182:185], v[46:49]
	v_mfma_f32_16x16x32_bf16 v[42:45], v[142:145], v[182:185], v[42:45]
	v_mfma_f32_16x16x32_bf16 v[30:33], v[134:137], v[190:193], v[30:33]
	v_mfma_f32_16x16x32_bf16 v[26:29], v[142:145], v[190:193], v[26:29]
	v_mfma_f32_16x16x32_bf16 v[14:17], v[134:137], v[200:203], v[14:17]
	v_mfma_f32_16x16x32_bf16 v[10:13], v[142:145], v[200:203], v[10:13]
	v_mfma_f32_16x16x32_bf16 v[54:57], v[146:149], v[162:165], v[54:57]
	v_mfma_f32_16x16x32_bf16 v[50:53], v[154:157], v[162:165], v[50:53]
	v_mfma_f32_16x16x32_bf16 v[38:41], v[146:149], v[178:181], v[38:41]
	v_mfma_f32_16x16x32_bf16 v[34:37], v[154:157], v[178:181], v[34:37]
	v_mfma_f32_16x16x32_bf16 v[22:25], v[146:149], v[186:189], v[22:25]
	v_mfma_f32_16x16x32_bf16 v[18:21], v[154:157], v[186:189], v[18:21]
	v_mfma_f32_16x16x32_bf16 v[6:9], v[146:149], v[194:197], v[6:9]
	v_mfma_f32_16x16x32_bf16 v[2:5], v[154:157], v[194:197], v[2:5]
	v_mfma_f32_16x16x32_bf16 v[54:57], v[150:153], v[174:177], v[54:57]
	v_mfma_f32_16x16x32_bf16 v[50:53], v[158:161], v[174:177], v[50:53]
	v_mfma_f32_16x16x32_bf16 v[38:41], v[150:153], v[182:185], v[38:41]
	v_mfma_f32_16x16x32_bf16 v[34:37], v[158:161], v[182:185], v[34:37]
	v_mfma_f32_16x16x32_bf16 v[22:25], v[150:153], v[190:193], v[22:25]
	v_mfma_f32_16x16x32_bf16 v[18:21], v[158:161], v[190:193], v[18:21]
	v_mfma_f32_16x16x32_bf16 v[6:9], v[150:153], v[200:203], v[6:9]
	v_mfma_f32_16x16x32_bf16 v[2:5], v[158:161], v[200:203], v[2:5]
	s_barrier
; #define PG8_WAIT_V(n) asm volatile("s_waitcnt vmcnt(" #n ")" ::: "memory")
; template <class Epi, bool ALIGN_EPI, bool SP2, class Hook>
; __device__ __forceinline__ void gemm_phase(LAS unsigned char* lds, const Gemm g, const StaticOrder& S, const Epi& E, Acc& acc, const bool fresh, const Hook& H, const int wave_id) {
;     ...
;         for (int t = t0; t < nt; t += 2) {
;             const bool last = (t == nt - 2);
;             const Src a1 = cA + (size_t)(t + 1) * kstep;
;             const Src a2 = last ? nA : cA + (size_t)(t + 2) * kstep, b2 = last ? nB : cB + (size_t)(t + 2) * kstep;
;             const Src a3 = a2 + kstep, b3 = b2 + kstep;
;             if (last && has_next) H(nxt);
;             if constexpr (SP2) {
;             PG8_TRIP_SP2(PG8_WAIT_V(8));
	s_setprio 0
	s_mov_b32 m0, s44
	s_nop 0
	buffer_load_dwordx4 v168, s[16:19], s62 offen lds
	s_mov_b32 m0, s36
	s_nop 0
	buffer_load_dwordx4 v170, s[16:19], s62 offen lds
	v_add_u32_e32 v0, 0x18000, v172
	ds_read_b128 v[130:133], v0
	ds_read_b128 v[134:137], v0 offset:1024
	ds_read_b128 v[138:141], v0 offset:2048
	ds_read_b128 v[142:145], v0 offset:3072
	v_add_u32_e32 v0, 0x1c000, v172
	ds_read_b128 v[146:149], v0
	ds_read_b128 v[150:153], v0 offset:1024
	ds_read_b128 v[154:157], v0 offset:2048
	ds_read_b128 v[158:161], v0 offset:3072
	s_add_i32 s62, s62, 0xc0000
	s_mov_b32 m0, s37
	ds_read_b128 v[162:165], v173 offset:32768
	ds_read_b128 v[174:177], v173 offset:33792
	ds_read_b128 v[178:181], v173 offset:34816
	ds_read_b128 v[182:185], v173 offset:35840
	ds_read_b128 v[186:189], v173 offset:36864
	ds_read_b128 v[190:193], v173 offset:37888
	ds_read_b128 v[194:197], v173 offset:38912
	ds_read_b128 v[200:203], v173 offset:39936
	buffer_load_dwordx4 v168, s[16:19], s62 offen lds
	s_mov_b32 m0, s38
	s_nop 0
	buffer_load_dwordx4 v170, s[16:19], s62 offen lds
	s_waitcnt vmcnt(8)
	s_waitcnt lgkmcnt(0)
	s_setprio 1
	s_barrier
	v_mfma_f32_16x16x32_bf16 v[126:129], v[130:133], v[162:165], v[126:129]
	v_mfma_f32_16x16x32_bf16 v[122:125], v[138:141], v[162:165], v[122:125]
	v_mfma_f32_16x16x32_bf16 v[110:113], v[130:133], v[178:181], v[110:113]
	v_mfma_f32_16x16x32_bf16 v[106:109], v[138:141], v[178:181], v[106:109]
	v_mfma_f32_16x16x32_bf16 v[94:97], v[130:133], v[186:189], v[94:97]
	v_mfma_f32_16x16x32_bf16 v[90:93], v[138:141], v[186:189], v[90:93]
	v_mfma_f32_16x16x32_bf16 v[78:81], v[130:133], v[194:197], v[78:81]
	v_mfma_f32_16x16x32_bf16 v[74:77], v[138:141], v[194:197], v[74:77]
	v_mfma_f32_16x16x32_bf16 v[126:129], v[134:137], v[174:177], v[126:129]
	v_mfma_f32_16x16x32_bf16 v[122:125], v[142:145], v[174:177], v[122:125]
	v_mfma_f32_16x16x32_bf16 v[110:113], v[134:137], v[182:185], v[110:113]
	v_mfma_f32_16x16x32_bf16 v[106:109], v[142:145], v[182:185], v[106:109]
	v_mfma_f32_16x16x32_bf16 v[94:97], v[134:137], v[190:193], v[94:97]
	v_mfma_f32_16x16x32_bf16 v[90:93], v[142:145], v[190:193], v[90:93]
	v_mfma_f32_16x16x32_bf16 v[78:81], v[134:137], v[200:203], v[78:81]
	v_mfma_f32_16x16x32_bf16 v[74:77], v[142:145], v[200:203], v[74:77]
	v_mfma_f32_16x16x32_bf16 v[118:121], v[146:149], v[162:165], v[118:121]
	v_mfma_f32_16x16x32_bf16 v[114:117], v[154:157], v[162:165], v[114:117]
	v_mfma_f32_16x16x32_bf16 v[102:105], v[146:149], v[178:181], v[102:105]
	v_mfma_f32_16x16x32_bf16 v[98:101], v[154:157], v[178:181], v[98:101]
	v_mfma_f32_16x16x32_bf16 v[86:89], v[146:149], v[186:189], v[86:89]
	v_mfma_f32_16x16x32_bf16 v[82:85], v[154:157], v[186:189], v[82:85]
	v_mfma_f32_16x16x32_bf16 v[70:73], v[146:149], v[194:197], v[70:73]
	v_mfma_f32_16x16x32_bf16 v[66:69], v[154:157], v[194:197], v[66:69]
	v_mfma_f32_16x16x32_bf16 v[118:121], v[150:153], v[174:177], v[118:121]
	v_mfma_f32_16x16x32_bf16 v[114:117], v[158:161], v[174:177], v[114:117]
	v_mfma_f32_16x16x32_bf16 v[102:105], v[150:153], v[182:185], v[102:105]
	v_mfma_f32_16x16x32_bf16 v[98:101], v[158:161], v[182:185], v[98:101]
	v_mfma_f32_16x16x32_bf16 v[86:89], v[150:153], v[190:193], v[86:89]
	v_mfma_f32_16x16x32_bf16 v[82:85], v[158:161], v[190:193], v[82:85]
	v_mfma_f32_16x16x32_bf16 v[70:73], v[150:153], v[200:203], v[70:73]
	v_mfma_f32_16x16x32_bf16 v[66:69], v[158:161], v[200:203], v[66:69]
	s_barrier
	s_setprio 0
	s_mov_b32 m0, s39
	s_or_b32 s62, s60, 0x80
	ds_read_b128 v[162:165], v173 offset:49152
	ds_read_b128 v[174:177], v173 offset:50176
	ds_read_b128 v[178:181], v173 offset:51200
	ds_read_b128 v[182:185], v173 offset:52224
	ds_read_b128 v[186:189], v173 offset:53248
	ds_read_b128 v[190:193], v173 offset:54272
	ds_read_b128 v[194:197], v173 offset:55296
	ds_read_b128 v[200:203], v173 offset:56320
	buffer_load_dwordx4 v169, s[12:15], s62 offen lds
	s_mov_b32 m0, s40
	s_add_i32 s60, s60, 0xb0080
	buffer_load_dwordx4 v171, s[12:15], s62 offen lds
	s_mov_b32 m0, s43
	s_nop 0
	buffer_load_dwordx4 v169, s[12:15], s60 offen lds
	s_mov_b32 m0, s42
	s_nop 0
	buffer_load_dwordx4 v171, s[12:15], s60 offen lds
	s_waitcnt vmcnt(6)
	s_waitcnt lgkmcnt(0)
	s_setprio 1
	s_barrier
	v_mfma_f32_16x16x32_bf16 v[62:65], v[130:133], v[162:165], v[62:65]
	v_mfma_f32_16x16x32_bf16 v[58:61], v[138:141], v[162:165], v[58:61]
	v_mfma_f32_16x16x32_bf16 v[46:49], v[130:133], v[178:181], v[46:49]
	v_mfma_f32_16x16x32_bf16 v[42:45], v[138:141], v[178:181], v[42:45]
	v_mfma_f32_16x16x32_bf16 v[30:33], v[130:133], v[186:189], v[30:33]
	v_mfma_f32_16x16x32_bf16 v[26:29], v[138:141], v[186:189], v[26:29]
	v_mfma_f32_16x16x32_bf16 v[14:17], v[130:133], v[194:197], v[14:17]
	v_mfma_f32_16x16x32_bf16 v[10:13], v[138:141], v[194:197], v[10:13]
	v_mfma_f32_16x16x32_bf16 v[62:65], v[134:137], v[174:177], v[62:65]
	v_mfma_f32_16x16x32_bf16 v[58:61], v[142:145], v[174:177], v[58:61]
	v_mfma_f32_16x16x32_bf16 v[46:49], v[134:137], v[182:185], v[46:49]
	v_mfma_f32_16x16x32_bf16 v[42:45], v[142:145], v[182:185], v[42:45]
	v_mfma_f32_16x16x32_bf16 v[30:33], v[134:137], v[190:193], v[30:33]
	v_mfma_f32_16x16x32_bf16 v[26:29], v[142:145], v[190:193], v[26:29]
	v_mfma_f32_16x16x32_bf16 v[14:17], v[134:137], v[200:203], v[14:17]
	v_mfma_f32_16x16x32_bf16 v[10:13], v[142:145], v[200:203], v[10:13]
	v_mfma_f32_16x16x32_bf16 v[54:57], v[146:149], v[162:165], v[54:57]
	v_mfma_f32_16x16x32_bf16 v[50:53], v[154:157], v[162:165], v[50:53]
	v_mfma_f32_16x16x32_bf16 v[38:41], v[146:149], v[178:181], v[38:41]
	v_mfma_f32_16x16x32_bf16 v[34:37], v[154:157], v[178:181], v[34:37]
	v_mfma_f32_16x16x32_bf16 v[22:25], v[146:149], v[186:189], v[22:25]
	v_mfma_f32_16x16x32_bf16 v[18:21], v[154:157], v[186:189], v[18:21]
	v_mfma_f32_16x16x32_bf16 v[6:9], v[146:149], v[194:197], v[6:9]
	v_mfma_f32_16x16x32_bf16 v[2:5], v[154:157], v[194:197], v[2:5]
	v_mfma_f32_16x16x32_bf16 v[54:57], v[150:153], v[174:177], v[54:57]
	v_mfma_f32_16x16x32_bf16 v[50:53], v[158:161], v[174:177], v[50:53]
	v_mfma_f32_16x16x32_bf16 v[38:41], v[150:153], v[182:185], v[38:41]
	v_mfma_f32_16x16x32_bf16 v[34:37], v[158:161], v[182:185], v[34:37]
	v_mfma_f32_16x16x32_bf16 v[22:25], v[150:153], v[190:193], v[22:25]
	v_mfma_f32_16x16x32_bf16 v[18:21], v[158:161], v[190:193], v[18:21]
	v_mfma_f32_16x16x32_bf16 v[6:9], v[150:153], v[200:203], v[6:9]
	v_mfma_f32_16x16x32_bf16 v[2:5], v[158:161], v[200:203], v[2:5]
	s_barrier
	s_setprio 0
	s_add_i32 s59, s59, 2
	s_addk_i32 s2, 0x100
	s_addk_i32 s3, 0x100
	s_cmp_gt_u32 s59, 41
	s_cbranch_scc0 .LBB0_1614
	s_mov_b32 m0, s41
	s_nop 0
	buffer_load_dwordx4 v168, s[16:19], s61 offen lds
	s_mov_b32 m0, s33
	s_nop 0
	buffer_load_dwordx4 v170, s[16:19], s61 offen lds
	v_readlane_b32 s2, v251, 45
	v_readlane_b32 s3, v251, 46
	s_and_b64 vcc, exec, s[2:3]
	s_cbranch_vccz .LBB0_1617
	s_barrier
